# UM2 + residual epilogues of the three x+=scale*acc GEMM phases: the first batch's four float atomics are deferred behind the second batch's loads (row sums parked in v240-243), so the second batch's v
# baseline (speedup 1.0000x reference)
; __device__ __forceinline__ float bflo(unsigned w) { return __uint_as_float(w << 16); }
; #define GAS __attribute__((address_space(1)))
;     __device__ __forceinline__ void operator()(const f32x4 (&acc)[2][2][4][2], const Unit& u, int wr, int wc, int fr_, int fq_) const {
;     ...
; #pragma unroll
;         for (int ab = 0; ab < 8 / MB; ++ab) {
;             const int ai = (ab * MB) >> 2, mb0 = (ab * MB) & 3;
;             u32x4 xw[MB][2], uw[MB][2];
; #pragma unroll
;             for (int mi = 0; mi < MB; ++mi)
; #pragma unroll
;                 for (int bj = 0; bj < 2; ++bj) { xw[mi][bj] = *(const GAS u32x4*)(xip + (size_t)(ai * 128 + (mb0 + mi) * 16) * DM + bj * 128);
;                     if (MODE == 1) uw[mi][bj] = *(const GAS u32x4*)(up + (size_t)(ai * 128 + (mb0 + mi) * 16) * DM + bj * 128); }
; #pragma unroll
;             for (int mi = 0; mi < MB; ++mi) {
;                 const int m = mb0 + mi;
;                 const size_t ro = (size_t)(ai * 128 + m * 16) * DM;
;                 const float rs = (MODE == 1) ? __builtin_amdgcn_rsqf(rsv[ai * 4 + m] * (1.0f / 1024.0f) + EPS) : 0.f; float ss = 0.f;
; #pragma unroll
;                 for (int bj = 0; bj < 2; ++bj) {
;                     const u32x4 xq = xw[mi][bj];
;                     f32x4 a0 = acc[ai][bj][m][0], a1 = acc[ai][bj][m][1];
;                     if (MODE == 1) {
;                         const u32x4 uu = uw[mi][bj];
;                         a0[0] = sigm_f(a0[0] * rs) * bflo(uu.x); a0[1] = sigm_f(a0[1] * rs) * bfhi(uu.x); a0[2] = sigm_f(a0[2] * rs) * bflo(uu.y); a0[3] = sigm_f(a0[3] * rs) * bfhi(uu.y);
;                         a1[0] = sigm_f(a1[0] * rs) * bflo(uu.z); a1[1] = sigm_f(a1[1] * rs) * bfhi(uu.z); a1[2] = sigm_f(a1[2] * rs) * bflo(uu.w); a1[3] = sigm_f(a1[3] * rs) * bfhi(uu.w);
;                     } else { a0 = a0 * scale; a1 = a1 * scale; }
;                     const f32x4 v0 = (f32x4){bflo(xq.x), bfhi(xq.x), bflo(xq.y), bfhi(xq.y)} + a0, v1 = (f32x4){bflo(xq.z), bfhi(xq.z), bflo(xq.w), bfhi(xq.w)} + a1;
;                     if (yout) { *(GAS f32x4*)(yp + ro + bj * 128) = v0; *(GAS f32x4*)(yp + ro + bj * 128 + 4) = v1; }
;                     else {
;                         u32x4 w; w.x = pk2(v0[0], v0[1]); w.y = pk2(v0[2], v0[3]); w.z = pk2(v1[0], v1[1]); w.w = pk2(v1[2], v1[3]);
;                         *(GAS u32x4*)(xop + ro + bj * 128) = w;
.LBB0_848:
	s_lshl_b32 s6, s66, 8
	v_mov_b32_e32 v203, v182
	s_add_i32 s6, s6, s57
	s_nop 0
	v_and_or_b32 v164, v203, 15, s6
	s_lshl_b32 s6, s65, 8
	v_ashrrev_i32_e32 v128, 1, v203
	s_or_b32 s6, s6, s60
	v_and_b32_e32 v128, -8, v128
	v_add_u32_e32 v128, s6, v128
	v_ashrrev_i32_e32 v165, 31, v164
	v_lshlrev_b64 v[130:131], 10, v[164:165]
	v_ashrrev_i32_e32 v129, 31, v128
	v_lshl_add_u64 v[128:129], v[130:131], 0, v[128:129]
	v_lshlrev_b64 v[166:167], 1, v[128:129]
	v_lshl_add_u64 v[168:169], s[12:13], 0, v[166:167]
	global_load_dwordx4 v[172:175], v[168:169], off
	global_load_dwordx4 v[176:179], v[168:169], off offset:256
	v_add_co_u32_e32 v128, vcc, s70, v168
	v_lshl_add_u64 v[166:167], s[10:11], 0, v[166:167]
	s_nop 0
	v_addc_co_u32_e32 v129, vcc, 0, v169, vcc
	v_add_co_u32_e32 v130, vcc, s37, v168
	v_cmp_gt_u32_e64 s[6:7], 16, v203
	s_nop 0
	v_addc_co_u32_e32 v131, vcc, 0, v169, vcc
	v_add_co_u32_e32 v180, vcc, s59, v168
	v_lshl_add_u64 v[164:165], v[164:165], 2, s[18:19]
	s_nop 0
	v_addc_co_u32_e32 v181, vcc, 0, v169, vcc
	global_load_dwordx4 v[148:151], v[128:129], off
	global_load_dwordx4 v[144:147], v[128:129], off offset:256
	global_load_dwordx4 v[140:143], v[130:131], off
	global_load_dwordx4 v[136:139], v[130:131], off offset:256
	global_load_dwordx4 v[132:135], v[180:181], off
	s_nop 0
	global_load_dwordx4 v[128:131], v[180:181], off offset:256
	s_waitcnt vmcnt(0)
	v_lshlrev_b32_e32 v180, 16, v172
	v_and_b32_e32 v181, 0xffff0000, v172
	v_lshlrev_b32_e32 v172, 16, v173
	v_and_b32_e32 v173, 0xffff0000, v173
	v_lshlrev_b32_e32 v206, 16, v176
	v_and_b32_e32 v207, 0xffff0000, v176
	v_lshlrev_b32_e32 v176, 16, v177
	v_and_b32_e32 v177, 0xffff0000, v177
	v_lshlrev_b32_e32 v204, 16, v174
	v_and_b32_e32 v205, 0xffff0000, v174
	v_lshlrev_b32_e32 v174, 16, v175
	v_and_b32_e32 v175, 0xffff0000, v175
	v_lshlrev_b32_e32 v208, 16, v178
	v_and_b32_e32 v209, 0xffff0000, v178
	v_lshlrev_b32_e32 v178, 16, v179
	v_and_b32_e32 v179, 0xffff0000, v179
	v_pk_fma_f32 v[126:127], v[126:127], 0.5, v[172:173] op_sel_hi:[1,0,1]
	v_pk_fma_f32 v[124:125], v[124:125], 0.5, v[180:181] op_sel_hi:[1,0,1]
	v_pk_fma_f32 v[118:119], v[118:119], 0.5, v[176:177] op_sel_hi:[1,0,1]
	v_pk_fma_f32 v[116:117], v[116:117], 0.5, v[206:207] op_sel_hi:[1,0,1]
	v_pk_fma_f32 v[122:123], v[122:123], 0.5, v[174:175] op_sel_hi:[1,0,1]
	v_pk_fma_f32 v[120:121], v[120:121], 0.5, v[204:205] op_sel_hi:[1,0,1]
	v_pk_fma_f32 v[172:173], v[114:115], 0.5, v[178:179] op_sel_hi:[1,0,1]
	v_pk_fma_f32 v[174:175], v[112:113], 0.5, v[208:209] op_sel_hi:[1,0,1]
	v_mul_f32_e32 v114, v125, v125
	v_mul_f32_e32 v115, v127, v127
	v_mul_f32_e32 v176, v117, v117
	v_mul_f32_e32 v177, v119, v119
	v_cvt_pk_bf16_f32 v112, v124, v125
	v_mul_f32_e32 v125, v121, v121
	v_mul_f32_e32 v178, v175, v175
	v_fmac_f32_e32 v114, v124, v124
	v_fmac_f32_e32 v115, v126, v126
	v_fmac_f32_e32 v176, v116, v116
	v_fmac_f32_e32 v177, v118, v118
	v_cvt_pk_bf16_f32 v113, v126, v127
	v_mul_f32_e32 v127, v123, v123
	v_mul_f32_e32 v179, v173, v173
	v_fmac_f32_e32 v125, v120, v120
	v_fmac_f32_e32 v178, v174, v174
	v_add_f32_e32 v114, v114, v115
	v_add_f32_e32 v115, v176, v177
	v_fmac_f32_e32 v127, v122, v122
	v_fmac_f32_e32 v179, v172, v172
	v_add_f32_e32 v114, v125, v114
	v_add_f32_e32 v115, v178, v115
	v_add_f32_e32 v114, v127, v114
	v_add_f32_e32 v115, v179, v115
	v_add_f32_e32 v124, v114, v115
	ds_bpermute_b32 v125, v184, v124
	v_cvt_pk_bf16_f32 v114, v120, v121
	v_cvt_pk_bf16_f32 v115, v122, v123
	global_store_dwordx4 v[166:167], v[112:115], off
	s_waitcnt lgkmcnt(0)
	s_nop 0
	v_add_f32_e32 v112, v124, v125
	ds_bpermute_b32 v113, v185, v112
	v_cvt_pk_bf16_f32 v114, v116, v117
	v_cvt_pk_bf16_f32 v115, v118, v119
	v_cvt_pk_bf16_f32 v116, v174, v175
	v_cvt_pk_bf16_f32 v117, v172, v173
	global_store_dwordx4 v[166:167], v[114:117], off offset:256
	s_and_saveexec_b64 s[24:25], s[6:7]
	s_cbranch_execz .LBB0_850
	s_waitcnt lgkmcnt(0)
	v_add_f32_e32 v112, v112, v113
	v_mov_b32_e32 v240, v112
.LBB0_850:
	s_or_b64 exec, exec, s[24:25]
	v_lshlrev_b32_e32 v112, 16, v148
	s_waitcnt lgkmcnt(0)
	v_and_b32_e32 v113, 0xffff0000, v148
	v_lshlrev_b32_e32 v114, 16, v149
	v_and_b32_e32 v115, 0xffff0000, v149
	v_pk_fma_f32 v[108:109], v[108:109], 0.5, v[112:113] op_sel_hi:[1,0,1]
	v_lshlrev_b32_e32 v112, 16, v150
	v_and_b32_e32 v113, 0xffff0000, v150
	v_pk_fma_f32 v[110:111], v[110:111], 0.5, v[114:115] op_sel_hi:[1,0,1]
	v_pk_fma_f32 v[112:113], v[104:105], 0.5, v[112:113] op_sel_hi:[1,0,1]
	v_cvt_pk_bf16_f32 v104, v108, v109
	v_mul_f32_e32 v109, v109, v109
	v_fmac_f32_e32 v109, v108, v108
	v_mul_f32_e32 v108, v111, v111
	v_fmac_f32_e32 v108, v110, v110
	v_lshlrev_b32_e32 v114, 16, v151
	v_and_b32_e32 v115, 0xffff0000, v151
	v_add_f32_e32 v108, v109, v108
	v_mul_f32_e32 v109, v113, v113
	v_pk_fma_f32 v[114:115], v[106:107], 0.5, v[114:115] op_sel_hi:[1,0,1]
	v_fmac_f32_e32 v109, v112, v112
	v_add_f32_e32 v108, v109, v108
	v_mul_f32_e32 v109, v115, v115
	v_fmac_f32_e32 v109, v114, v114
	v_cvt_pk_bf16_f32 v105, v110, v111
	v_cvt_pk_bf16_f32 v106, v112, v113
	v_add_f32_e32 v112, v109, v108
	v_lshlrev_b32_e32 v108, 16, v144
	v_and_b32_e32 v109, 0xffff0000, v144
	v_lshlrev_b32_e32 v110, 16, v145
	v_and_b32_e32 v111, 0xffff0000, v145
	v_pk_fma_f32 v[102:103], v[102:103], 0.5, v[110:111] op_sel_hi:[1,0,1]
	v_pk_fma_f32 v[100:101], v[100:101], 0.5, v[108:109] op_sel_hi:[1,0,1]
	v_lshlrev_b32_e32 v108, 16, v146
	v_and_b32_e32 v109, 0xffff0000, v146
	v_pk_fma_f32 v[108:109], v[96:97], 0.5, v[108:109] op_sel_hi:[1,0,1]
	v_mul_f32_e32 v96, v101, v101
	v_mul_f32_e32 v97, v103, v103
	v_fmac_f32_e32 v96, v100, v100
	v_fmac_f32_e32 v97, v102, v102
	v_lshlrev_b32_e32 v110, 16, v147
	v_and_b32_e32 v111, 0xffff0000, v147
	v_add_f32_e32 v96, v96, v97
	v_mul_f32_e32 v97, v109, v109
	v_pk_fma_f32 v[110:111], v[98:99], 0.5, v[110:111] op_sel_hi:[1,0,1]
	v_fmac_f32_e32 v97, v108, v108
	v_add_f32_e32 v96, v97, v96
	v_mul_f32_e32 v97, v111, v111
	v_fmac_f32_e32 v97, v110, v110
	v_add_f32_e32 v96, v97, v96
	v_add_f32_e32 v96, v112, v96
	ds_bpermute_b32 v97, v184, v96
	v_add_co_u32_e32 v112, vcc, s70, v166
	v_cvt_pk_bf16_f32 v107, v114, v115
	s_nop 0
	v_addc_co_u32_e32 v113, vcc, 0, v167, vcc
	s_waitcnt lgkmcnt(0)
	v_add_f32_e32 v96, v96, v97
	ds_bpermute_b32 v97, v185, v96
	v_cvt_pk_bf16_f32 v98, v100, v101
	v_cvt_pk_bf16_f32 v99, v102, v103
	v_cvt_pk_bf16_f32 v100, v108, v109
	v_cvt_pk_bf16_f32 v101, v110, v111
	global_store_dwordx4 v[112:113], v[104:107], off
	global_store_dwordx4 v[112:113], v[98:101], off offset:256
	s_and_saveexec_b64 s[24:25], s[6:7]
	s_cbranch_execz .LBB0_852
	s_waitcnt lgkmcnt(0)
	v_add_f32_e32 v96, v96, v97
	v_mov_b32_e32 v241, v96
; __device__ __forceinline__ unsigned pk2(float lo, float hi) { f32x2 v = {lo, hi}; bf16x2_t b = __builtin_convertvector(v, bf16x2_t); return __builtin_bit_cast(unsigned, b); }
; __device__ __forceinline__ float bflo(unsigned w) { return __uint_as_float(w << 16); }
;     __device__ __forceinline__ void operator()(const f32x4 (&acc)[2][2][4][2], const Unit& u, int wr, int wc, int fr_, int fq_) const {
;     ...
;             for (int mi = 0; mi < MB; ++mi) {
;                 const int m = mb0 + mi;
;                 const size_t ro = (size_t)(ai * 128 + m * 16) * DM;
;                 const float rs = (MODE == 1) ? __builtin_amdgcn_rsqf(rsv[ai * 4 + m] * (1.0f / 1024.0f) + EPS) : 0.f; float ss = 0.f;
; #pragma unroll
;                 for (int bj = 0; bj < 2; ++bj) {
;                     const u32x4 xq = xw[mi][bj];
;                     f32x4 a0 = acc[ai][bj][m][0], a1 = acc[ai][bj][m][1];
;                     if (MODE == 1) {
;                         const u32x4 uu = uw[mi][bj];
;                         a0[0] = sigm_f(a0[0] * rs) * bflo(uu.x); a0[1] = sigm_f(a0[1] * rs) * bfhi(uu.x); a0[2] = sigm_f(a0[2] * rs) * bflo(uu.y); a0[3] = sigm_f(a0[3] * rs) * bfhi(uu.y);
;                         a1[0] = sigm_f(a1[0] * rs) * bflo(uu.z); a1[1] = sigm_f(a1[1] * rs) * bfhi(uu.z); a1[2] = sigm_f(a1[2] * rs) * bflo(uu.w); a1[3] = sigm_f(a1[3] * rs) * bfhi(uu.w);
;                     } else { a0 = a0 * scale; a1 = a1 * scale; }
;                     const f32x4 v0 = (f32x4){bflo(xq.x), bfhi(xq.x), bflo(xq.y), bfhi(xq.y)} + a0, v1 = (f32x4){bflo(xq.z), bfhi(xq.z), bflo(xq.w), bfhi(xq.w)} + a1;
;                     if (yout) { *(GAS f32x4*)(yp + ro + bj * 128) = v0; *(GAS f32x4*)(yp + ro + bj * 128 + 4) = v1; }
;                     else {
;                         u32x4 w; w.x = pk2(v0[0], v0[1]); w.y = pk2(v0[2], v0[3]); w.z = pk2(v1[0], v1[1]); w.w = pk2(v1[2], v1[3]);
;                         *(GAS u32x4*)(xop + ro + bj * 128) = w;
;                         ss += (v0[0] * v0[0] + v0[1] * v0[1]) + (v0[2] * v0[2] + v0[3] * v0[3]) + (v1[0] * v1[0] + v1[1] * v1[1]) + (v1[2] * v1[2] + v1[3] * v1[3]);
;                     }
;                 }
;                 if (!yout) { ss += __shfl_xor(ss, 16); ss += __shfl_xor(ss, 32);
;                     if (fq == 0) __hip_atomic_fetch_add(sn + ai * 128 + m * 16, ss, __ATOMIC_RELAXED, __HIP_MEMORY_SCOPE_AGENT); }
.LBB0_852:
	s_or_b64 exec, exec, s[24:25]
	v_lshlrev_b32_e32 v96, 16, v140
	s_waitcnt lgkmcnt(0)
	v_and_b32_e32 v97, 0xffff0000, v140
	v_lshlrev_b32_e32 v98, 16, v141
	v_and_b32_e32 v99, 0xffff0000, v141
	v_pk_fma_f32 v[92:93], v[92:93], 0.5, v[96:97] op_sel_hi:[1,0,1]
	v_lshlrev_b32_e32 v96, 16, v142
	v_and_b32_e32 v97, 0xffff0000, v142
	v_pk_fma_f32 v[94:95], v[94:95], 0.5, v[98:99] op_sel_hi:[1,0,1]
	v_pk_fma_f32 v[96:97], v[88:89], 0.5, v[96:97] op_sel_hi:[1,0,1]
	v_cvt_pk_bf16_f32 v88, v92, v93
	v_mul_f32_e32 v93, v93, v93
	v_fmac_f32_e32 v93, v92, v92
	v_mul_f32_e32 v92, v95, v95
	v_fmac_f32_e32 v92, v94, v94
	v_lshlrev_b32_e32 v98, 16, v143
	v_and_b32_e32 v99, 0xffff0000, v143
	v_add_f32_e32 v92, v93, v92
	v_mul_f32_e32 v93, v97, v97
	v_pk_fma_f32 v[98:99], v[90:91], 0.5, v[98:99] op_sel_hi:[1,0,1]
	v_fmac_f32_e32 v93, v96, v96
	v_add_f32_e32 v92, v93, v92
	v_mul_f32_e32 v93, v99, v99
	v_fmac_f32_e32 v93, v98, v98
	v_cvt_pk_bf16_f32 v89, v94, v95
	v_cvt_pk_bf16_f32 v90, v96, v97
	v_add_f32_e32 v96, v93, v92
	v_lshlrev_b32_e32 v92, 16, v136
	v_and_b32_e32 v93, 0xffff0000, v136
	v_lshlrev_b32_e32 v94, 16, v137
	v_and_b32_e32 v95, 0xffff0000, v137
	v_pk_fma_f32 v[86:87], v[86:87], 0.5, v[94:95] op_sel_hi:[1,0,1]
	v_pk_fma_f32 v[84:85], v[84:85], 0.5, v[92:93] op_sel_hi:[1,0,1]
	v_lshlrev_b32_e32 v92, 16, v138
	v_and_b32_e32 v93, 0xffff0000, v138
	v_pk_fma_f32 v[92:93], v[80:81], 0.5, v[92:93] op_sel_hi:[1,0,1]
	v_mul_f32_e32 v80, v85, v85
	v_mul_f32_e32 v81, v87, v87
	v_fmac_f32_e32 v80, v84, v84
	v_fmac_f32_e32 v81, v86, v86
	v_lshlrev_b32_e32 v94, 16, v139
	v_and_b32_e32 v95, 0xffff0000, v139
	v_add_f32_e32 v80, v80, v81
	v_mul_f32_e32 v81, v93, v93
	v_pk_fma_f32 v[94:95], v[82:83], 0.5, v[94:95] op_sel_hi:[1,0,1]
	v_fmac_f32_e32 v81, v92, v92
	v_add_f32_e32 v80, v81, v80
	v_mul_f32_e32 v81, v95, v95
	v_fmac_f32_e32 v81, v94, v94
	v_add_f32_e32 v80, v81, v80
	v_add_f32_e32 v80, v96, v80
	ds_bpermute_b32 v81, v184, v80
	v_add_co_u32_e32 v96, vcc, s37, v166
	v_cvt_pk_bf16_f32 v91, v98, v99
	s_nop 0
	v_addc_co_u32_e32 v97, vcc, 0, v167, vcc
	s_waitcnt lgkmcnt(0)
	v_add_f32_e32 v80, v80, v81
	ds_bpermute_b32 v81, v185, v80
	v_cvt_pk_bf16_f32 v82, v84, v85
	v_cvt_pk_bf16_f32 v83, v86, v87
	v_cvt_pk_bf16_f32 v84, v92, v93
	v_cvt_pk_bf16_f32 v85, v94, v95
	global_store_dwordx4 v[96:97], v[88:91], off
	global_store_dwordx4 v[96:97], v[82:85], off offset:256
	s_and_saveexec_b64 s[24:25], s[6:7]
	s_cbranch_execz .LBB0_854
	s_waitcnt lgkmcnt(0)
	v_add_f32_e32 v80, v80, v81
	v_mov_b32_e32 v242, v80
.LBB0_854:
	s_or_b64 exec, exec, s[24:25]
	v_lshlrev_b32_e32 v80, 16, v132
	s_waitcnt lgkmcnt(0)
	v_and_b32_e32 v81, 0xffff0000, v132
	v_lshlrev_b32_e32 v82, 16, v133
	v_and_b32_e32 v83, 0xffff0000, v133
	v_pk_fma_f32 v[76:77], v[76:77], 0.5, v[80:81] op_sel_hi:[1,0,1]
	v_lshlrev_b32_e32 v80, 16, v134
	v_and_b32_e32 v81, 0xffff0000, v134
	v_pk_fma_f32 v[78:79], v[78:79], 0.5, v[82:83] op_sel_hi:[1,0,1]
	v_pk_fma_f32 v[80:81], v[72:73], 0.5, v[80:81] op_sel_hi:[1,0,1]
	v_cvt_pk_bf16_f32 v72, v76, v77
	v_mul_f32_e32 v77, v77, v77
	v_fmac_f32_e32 v77, v76, v76
	v_mul_f32_e32 v76, v79, v79
	v_fmac_f32_e32 v76, v78, v78
	v_lshlrev_b32_e32 v82, 16, v135
	v_and_b32_e32 v83, 0xffff0000, v135
	v_add_f32_e32 v76, v77, v76
	v_mul_f32_e32 v77, v81, v81
	v_pk_fma_f32 v[82:83], v[74:75], 0.5, v[82:83] op_sel_hi:[1,0,1]
	v_fmac_f32_e32 v77, v80, v80
	v_add_f32_e32 v76, v77, v76
	v_mul_f32_e32 v77, v83, v83
	v_fmac_f32_e32 v77, v82, v82
	v_cvt_pk_bf16_f32 v73, v78, v79
	v_cvt_pk_bf16_f32 v74, v80, v81
	v_add_f32_e32 v80, v77, v76
	v_lshlrev_b32_e32 v76, 16, v128
	v_and_b32_e32 v77, 0xffff0000, v128
	v_lshlrev_b32_e32 v78, 16, v129
	v_and_b32_e32 v79, 0xffff0000, v129
	v_pk_fma_f32 v[70:71], v[70:71], 0.5, v[78:79] op_sel_hi:[1,0,1]
	v_pk_fma_f32 v[68:69], v[68:69], 0.5, v[76:77] op_sel_hi:[1,0,1]
	v_lshlrev_b32_e32 v76, 16, v130
	v_and_b32_e32 v77, 0xffff0000, v130
	v_pk_fma_f32 v[76:77], v[64:65], 0.5, v[76:77] op_sel_hi:[1,0,1]
	v_mul_f32_e32 v64, v69, v69
	v_mul_f32_e32 v65, v71, v71
	v_fmac_f32_e32 v64, v68, v68
	v_fmac_f32_e32 v65, v70, v70
	v_lshlrev_b32_e32 v78, 16, v131
	v_and_b32_e32 v79, 0xffff0000, v131
	v_add_f32_e32 v64, v64, v65
	v_mul_f32_e32 v65, v77, v77
	v_pk_fma_f32 v[78:79], v[66:67], 0.5, v[78:79] op_sel_hi:[1,0,1]
	v_fmac_f32_e32 v65, v76, v76
	v_add_f32_e32 v64, v65, v64
	v_mul_f32_e32 v65, v79, v79
	v_fmac_f32_e32 v65, v78, v78
	v_add_f32_e32 v64, v65, v64
	v_add_f32_e32 v64, v80, v64
	ds_bpermute_b32 v65, v184, v64
	v_add_co_u32_e32 v80, vcc, s59, v166
	v_cvt_pk_bf16_f32 v75, v82, v83
	s_nop 0
	v_addc_co_u32_e32 v81, vcc, 0, v167, vcc
	s_waitcnt lgkmcnt(0)
	v_add_f32_e32 v64, v64, v65
	ds_bpermute_b32 v65, v185, v64
	v_cvt_pk_bf16_f32 v66, v68, v69
	v_cvt_pk_bf16_f32 v67, v70, v71
	v_cvt_pk_bf16_f32 v68, v76, v77
	v_cvt_pk_bf16_f32 v69, v78, v79
	global_store_dwordx4 v[80:81], v[72:75], off
	global_store_dwordx4 v[80:81], v[66:69], off offset:256
	s_and_saveexec_b64 s[24:25], s[6:7]
	s_cbranch_execz .LBB0_856
	s_waitcnt lgkmcnt(0)
	v_add_f32_e32 v64, v64, v65
	v_mov_b32_e32 v243, v64

; __device__ __forceinline__ unsigned pk2(float lo, float hi) { f32x2 v = {lo, hi}; bf16x2_t b = __builtin_convertvector(v, bf16x2_t); return __builtin_bit_cast(unsigned, b); }
; __device__ __forceinline__ float bflo(unsigned w) { return __uint_as_float(w << 16); }
;     __device__ __forceinline__ void operator()(const f32x4 (&acc)[2][2][4][2], const Unit& u, int wr, int wc, int fr_, int fq_) const {
;     ...
;             for (int mi = 0; mi < MB; ++mi) {
;                 const int m = mb0 + mi;
;                 const size_t ro = (size_t)(ai * 128 + m * 16) * DM;
;                 const float rs = (MODE == 1) ? __builtin_amdgcn_rsqf(rsv[ai * 4 + m] * (1.0f / 1024.0f) + EPS) : 0.f; float ss = 0.f;
; #pragma unroll
;                 for (int bj = 0; bj < 2; ++bj) {
;                     const u32x4 xq = xw[mi][bj];
;                     f32x4 a0 = acc[ai][bj][m][0], a1 = acc[ai][bj][m][1];
;                     if (MODE == 1) {
;                         const u32x4 uu = uw[mi][bj];
;                         a0[0] = sigm_f(a0[0] * rs) * bflo(uu.x); a0[1] = sigm_f(a0[1] * rs) * bfhi(uu.x); a0[2] = sigm_f(a0[2] * rs) * bflo(uu.y); a0[3] = sigm_f(a0[3] * rs) * bfhi(uu.y);
;                         a1[0] = sigm_f(a1[0] * rs) * bflo(uu.z); a1[1] = sigm_f(a1[1] * rs) * bfhi(uu.z); a1[2] = sigm_f(a1[2] * rs) * bflo(uu.w); a1[3] = sigm_f(a1[3] * rs) * bfhi(uu.w);
;                     } else { a0 = a0 * scale; a1 = a1 * scale; }
;                     const f32x4 v0 = (f32x4){bflo(xq.x), bfhi(xq.x), bflo(xq.y), bfhi(xq.y)} + a0, v1 = (f32x4){bflo(xq.z), bfhi(xq.z), bflo(xq.w), bfhi(xq.w)} + a1;
;                     if (yout) { *(GAS f32x4*)(yp + ro + bj * 128) = v0; *(GAS f32x4*)(yp + ro + bj * 128 + 4) = v1; }
;                     else {
;                         u32x4 w; w.x = pk2(v0[0], v0[1]); w.y = pk2(v0[2], v0[3]); w.z = pk2(v1[0], v1[1]); w.w = pk2(v1[2], v1[3]);
;                         *(GAS u32x4*)(xop + ro + bj * 128) = w;
;                         ss += (v0[0] * v0[0] + v0[1] * v0[1]) + (v0[2] * v0[2] + v0[3] * v0[3]) + (v1[0] * v1[0] + v1[1] * v1[1]) + (v1[2] * v1[2] + v1[3] * v1[3]);
;                     }
;                 }
;                 if (!yout) { ss += __shfl_xor(ss, 16); ss += __shfl_xor(ss, 32);
;                     if (fq == 0) __hip_atomic_fetch_add(sn + ai * 128 + m * 16, ss, __ATOMIC_RELAXED, __HIP_MEMORY_SCOPE_AGENT); }
.LBB0_862:
	s_or_b64 exec, exec, s[24:25]
	s_waitcnt vmcnt(7)
	v_lshlrev_b32_e32 v16, 16, v68
	s_waitcnt lgkmcnt(0)
	v_and_b32_e32 v17, 0xffff0000, v68
	v_lshlrev_b32_e32 v18, 16, v69
	v_and_b32_e32 v19, 0xffff0000, v69
	v_pk_fma_f32 v[12:13], v[12:13], 0.5, v[16:17] op_sel_hi:[1,0,1]
	v_lshlrev_b32_e32 v16, 16, v70
	v_and_b32_e32 v17, 0xffff0000, v70
	v_pk_fma_f32 v[14:15], v[14:15], 0.5, v[18:19] op_sel_hi:[1,0,1]
	v_pk_fma_f32 v[16:17], v[8:9], 0.5, v[16:17] op_sel_hi:[1,0,1]
	v_cvt_pk_bf16_f32 v8, v12, v13
	v_mul_f32_e32 v13, v13, v13
	v_fmac_f32_e32 v13, v12, v12
	v_mul_f32_e32 v12, v15, v15
	v_fmac_f32_e32 v12, v14, v14
	v_lshlrev_b32_e32 v18, 16, v71
	v_and_b32_e32 v19, 0xffff0000, v71
	v_add_f32_e32 v12, v13, v12
	v_mul_f32_e32 v13, v17, v17
	v_pk_fma_f32 v[18:19], v[10:11], 0.5, v[18:19] op_sel_hi:[1,0,1]
	v_fmac_f32_e32 v13, v16, v16
	v_add_f32_e32 v12, v13, v12
	v_mul_f32_e32 v13, v19, v19
	v_fmac_f32_e32 v13, v18, v18
	v_cvt_pk_bf16_f32 v9, v14, v15
	v_cvt_pk_bf16_f32 v10, v16, v17
	v_add_f32_e32 v16, v13, v12
	s_waitcnt vmcnt(6)
	s_and_saveexec_b64 s[24:25], s[6:7]
	global_atomic_add_f32 v[164:165], v240, off
	global_atomic_add_f32 v[164:165], v241, off offset:64
	global_atomic_add_f32 v[164:165], v242, off offset:128
	global_atomic_add_f32 v[164:165], v243, off offset:192
	s_or_b64 exec, exec, s[24:25]
	v_lshlrev_b32_e32 v12, 16, v64
	v_and_b32_e32 v13, 0xffff0000, v64
	v_lshlrev_b32_e32 v14, 16, v65
	v_and_b32_e32 v15, 0xffff0000, v65
	v_pk_fma_f32 v[6:7], v[6:7], 0.5, v[14:15] op_sel_hi:[1,0,1]
	v_pk_fma_f32 v[4:5], v[4:5], 0.5, v[12:13] op_sel_hi:[1,0,1]
	v_lshlrev_b32_e32 v12, 16, v66
	v_and_b32_e32 v13, 0xffff0000, v66
	v_pk_fma_f32 v[12:13], v[0:1], 0.5, v[12:13] op_sel_hi:[1,0,1]
	v_mul_f32_e32 v0, v5, v5
	v_mul_f32_e32 v1, v7, v7
	v_fmac_f32_e32 v0, v4, v4
	v_fmac_f32_e32 v1, v6, v6
	v_lshlrev_b32_e32 v14, 16, v67
	v_and_b32_e32 v15, 0xffff0000, v67
	v_add_f32_e32 v0, v0, v1
	v_mul_f32_e32 v1, v13, v13
	v_pk_fma_f32 v[14:15], v[2:3], 0.5, v[14:15] op_sel_hi:[1,0,1]
	v_fmac_f32_e32 v1, v12, v12
	v_add_f32_e32 v0, v1, v0
	v_mul_f32_e32 v1, v15, v15
	v_fmac_f32_e32 v1, v14, v14
	v_add_f32_e32 v0, v1, v0
	v_add_f32_e32 v0, v16, v0
	ds_bpermute_b32 v1, v184, v0
	s_mov_b32 s21, 0x58000
	v_add_co_u32_e32 v16, vcc, s21, v166
	v_cvt_pk_bf16_f32 v11, v18, v19
	s_waitcnt lgkmcnt(0)
	v_add_f32_e32 v0, v0, v1
	ds_bpermute_b32 v1, v185, v0
	v_addc_co_u32_e32 v17, vcc, 0, v167, vcc
	v_cvt_pk_bf16_f32 v2, v4, v5
	v_cvt_pk_bf16_f32 v3, v6, v7
	v_cvt_pk_bf16_f32 v4, v12, v13
	v_cvt_pk_bf16_f32 v5, v14, v15
	global_store_dwordx4 v[16:17], v[8:11], off
	global_store_dwordx4 v[16:17], v[2:5], off offset:256
	s_and_saveexec_b64 s[24:25], s[6:7]
	s_cbranch_execz .LBB0_864
	s_waitcnt lgkmcnt(0)
	v_add_f32_e32 v0, v0, v1
	global_atomic_add_f32 v[164:165], v0, off offset:704

; __device__ __forceinline__ float bflo(unsigned w) { return __uint_as_float(w << 16); }
; #define GAS __attribute__((address_space(1)))
;     __device__ __forceinline__ void operator()(const f32x4 (&acc)[2][2][4][2], const Unit& u, int wr, int wc, int fr_, int fq_) const {
;     ...
; #pragma unroll
;         for (int ab = 0; ab < 8 / MB; ++ab) {
;             const int ai = (ab * MB) >> 2, mb0 = (ab * MB) & 3;
;             u32x4 xw[MB][2], uw[MB][2];
; #pragma unroll
;             for (int mi = 0; mi < MB; ++mi)
; #pragma unroll
;                 for (int bj = 0; bj < 2; ++bj) { xw[mi][bj] = *(const GAS u32x4*)(xip + (size_t)(ai * 128 + (mb0 + mi) * 16) * DM + bj * 128);
;                     if (MODE == 1) uw[mi][bj] = *(const GAS u32x4*)(up + (size_t)(ai * 128 + (mb0 + mi) * 16) * DM + bj * 128); }
; #pragma unroll
;             for (int mi = 0; mi < MB; ++mi) {
;                 const int m = mb0 + mi;
;                 const size_t ro = (size_t)(ai * 128 + m * 16) * DM;
;                 const float rs = (MODE == 1) ? __builtin_amdgcn_rsqf(rsv[ai * 4 + m] * (1.0f / 1024.0f) + EPS) : 0.f; float ss = 0.f;
; #pragma unroll
;                 for (int bj = 0; bj < 2; ++bj) {
;                     const u32x4 xq = xw[mi][bj];
;                     f32x4 a0 = acc[ai][bj][m][0], a1 = acc[ai][bj][m][1];
;                     if (MODE == 1) {
;                         const u32x4 uu = uw[mi][bj];
;                         a0[0] = sigm_f(a0[0] * rs) * bflo(uu.x); a0[1] = sigm_f(a0[1] * rs) * bfhi(uu.x); a0[2] = sigm_f(a0[2] * rs) * bflo(uu.y); a0[3] = sigm_f(a0[3] * rs) * bfhi(uu.y);
;                         a1[0] = sigm_f(a1[0] * rs) * bflo(uu.z); a1[1] = sigm_f(a1[1] * rs) * bfhi(uu.z); a1[2] = sigm_f(a1[2] * rs) * bflo(uu.w); a1[3] = sigm_f(a1[3] * rs) * bfhi(uu.w);
;                     } else { a0 = a0 * scale; a1 = a1 * scale; }
;                     const f32x4 v0 = (f32x4){bflo(xq.x), bfhi(xq.x), bflo(xq.y), bfhi(xq.y)} + a0, v1 = (f32x4){bflo(xq.z), bfhi(xq.z), bflo(xq.w), bfhi(xq.w)} + a1;
;                     if (yout) { *(GAS f32x4*)(yp + ro + bj * 128) = v0; *(GAS f32x4*)(yp + ro + bj * 128 + 4) = v1; }
;                     else {
;                         u32x4 w; w.x = pk2(v0[0], v0[1]); w.y = pk2(v0[2], v0[3]); w.z = pk2(v1[0], v1[1]); w.w = pk2(v1[2], v1[3]);
;                         *(GAS u32x4*)(xop + ro + bj * 128) = w;
.LBB0_1959:
	s_lshl_b32 s4, s25, 8
	v_mov_b32_e32 v180, v182
	s_add_i32 s4, s4, s56
	s_nop 0
	v_and_or_b32 v164, v180, 15, s4
	s_lshl_b32 s4, s24, 8
	v_ashrrev_i32_e32 v128, 1, v180
	s_or_b32 s4, s4, s57
	v_and_b32_e32 v128, -8, v128
	v_ashrrev_i32_e32 v165, 31, v164
	v_add_u32_e32 v128, s4, v128
	v_lshlrev_b64 v[130:131], 11, v[164:165]
	v_ashrrev_i32_e32 v129, 31, v128
	v_lshl_add_u64 v[130:131], s[8:9], 0, v[130:131]
	v_lshl_add_u64 v[166:167], v[128:129], 1, v[130:131]
	global_load_dwordx4 v[170:173], v[166:167], off
	global_load_dwordx4 v[174:177], v[166:167], off offset:256
	v_add_co_u32_e32 v128, vcc, s70, v166
	v_cmp_gt_u32_e64 s[4:5], 16, v180
	s_nop 0
	v_addc_co_u32_e32 v129, vcc, 0, v167, vcc
	v_add_co_u32_e32 v130, vcc, s37, v166
	v_lshl_add_u64 v[164:165], v[164:165], 2, s[10:11]
	s_nop 0
	v_addc_co_u32_e32 v131, vcc, 0, v167, vcc
	v_add_co_u32_e32 v178, vcc, s59, v166
	s_waitcnt vmcnt(0)
	v_lshlrev_b32_e32 v180, 16, v172
	v_addc_co_u32_e32 v179, vcc, 0, v167, vcc
	global_load_dwordx4 v[148:151], v[128:129], off
	global_load_dwordx4 v[144:147], v[128:129], off offset:256
	global_load_dwordx4 v[140:143], v[130:131], off
	global_load_dwordx4 v[136:139], v[130:131], off offset:256
	global_load_dwordx4 v[132:135], v[178:179], off
	s_nop 0
	global_load_dwordx4 v[128:131], v[178:179], off offset:256
	v_lshlrev_b32_e32 v178, 16, v170
	v_and_b32_e32 v179, 0xffff0000, v170
	v_lshlrev_b32_e32 v170, 16, v171
	v_and_b32_e32 v171, 0xffff0000, v171
	v_lshlrev_b32_e32 v204, 16, v174
	v_and_b32_e32 v205, 0xffff0000, v174
	v_lshlrev_b32_e32 v174, 16, v175
	v_and_b32_e32 v175, 0xffff0000, v175
	v_and_b32_e32 v181, 0xffff0000, v172
	v_lshlrev_b32_e32 v172, 16, v173
	v_and_b32_e32 v173, 0xffff0000, v173
	v_lshlrev_b32_e32 v206, 16, v176
	v_and_b32_e32 v207, 0xffff0000, v176
	v_lshlrev_b32_e32 v176, 16, v177
	v_and_b32_e32 v177, 0xffff0000, v177
	v_pk_add_f32 v[126:127], v[126:127], v[170:171]
	v_pk_add_f32 v[124:125], v[124:125], v[178:179]
	v_pk_add_f32 v[118:119], v[118:119], v[174:175]
	v_pk_add_f32 v[116:117], v[116:117], v[204:205]
	v_pk_add_f32 v[122:123], v[122:123], v[172:173]
	v_pk_add_f32 v[120:121], v[120:121], v[180:181]
	v_pk_add_f32 v[170:171], v[114:115], v[176:177]
	v_pk_add_f32 v[172:173], v[112:113], v[206:207]
	v_mul_f32_e32 v114, v125, v125
	v_mul_f32_e32 v115, v127, v127
	v_mul_f32_e32 v174, v117, v117
	v_mul_f32_e32 v175, v119, v119
	v_cvt_pk_bf16_f32 v112, v124, v125
	v_mul_f32_e32 v125, v121, v121
	v_mul_f32_e32 v176, v173, v173
	v_fmac_f32_e32 v114, v124, v124
	v_fmac_f32_e32 v115, v126, v126
	v_fmac_f32_e32 v174, v116, v116
	v_fmac_f32_e32 v175, v118, v118
	v_cvt_pk_bf16_f32 v113, v126, v127
	v_mul_f32_e32 v127, v123, v123
	v_mul_f32_e32 v177, v171, v171
	v_fmac_f32_e32 v125, v120, v120
	v_fmac_f32_e32 v176, v172, v172
	v_add_f32_e32 v114, v114, v115
	v_add_f32_e32 v115, v174, v175
	v_fmac_f32_e32 v127, v122, v122
	v_fmac_f32_e32 v177, v170, v170
	v_add_f32_e32 v114, v125, v114
	v_add_f32_e32 v115, v176, v115
	v_add_f32_e32 v114, v127, v114
	v_add_f32_e32 v115, v177, v115
	v_add_f32_e32 v124, v114, v115
	ds_bpermute_b32 v125, v184, v124
	v_cvt_pk_bf16_f32 v114, v120, v121
	v_cvt_pk_bf16_f32 v115, v122, v123
	global_store_dwordx4 v[166:167], v[112:115], off
	s_waitcnt lgkmcnt(0)
	s_nop 0
	v_add_f32_e32 v112, v124, v125
	ds_bpermute_b32 v113, v185, v112
	v_cvt_pk_bf16_f32 v114, v116, v117
	v_cvt_pk_bf16_f32 v115, v118, v119
	v_cvt_pk_bf16_f32 v116, v172, v173
	v_cvt_pk_bf16_f32 v117, v170, v171
	global_store_dwordx4 v[166:167], v[114:117], off offset:256
	s_and_saveexec_b64 s[24:25], s[4:5]
	s_cbranch_execz .LBB0_1961
	s_waitcnt lgkmcnt(0)
	v_add_f32_e32 v112, v112, v113
	v_mov_b32_e32 v240, v112
.LBB0_1961:
	s_or_b64 exec, exec, s[24:25]
	s_waitcnt vmcnt(7)
	v_lshlrev_b32_e32 v116, 16, v148
	v_and_b32_e32 v117, 0xffff0000, v148
	v_lshlrev_b32_e32 v118, 16, v149
	v_and_b32_e32 v119, 0xffff0000, v149
	v_pk_add_f32 v[110:111], v[110:111], v[118:119]
	v_pk_add_f32 v[108:109], v[108:109], v[116:117]
	v_lshlrev_b32_e32 v116, 16, v150
	v_and_b32_e32 v117, 0xffff0000, v150
	v_lshlrev_b32_e32 v118, 16, v151
	v_and_b32_e32 v119, 0xffff0000, v151
	v_pk_add_f32 v[118:119], v[106:107], v[118:119]
	v_pk_add_f32 v[106:107], v[104:105], v[116:117]
	v_cvt_pk_bf16_f32 v104, v108, v109
	v_mul_f32_e32 v109, v109, v109
	v_fmac_f32_e32 v109, v108, v108
	v_mul_f32_e32 v108, v111, v111
	v_fmac_f32_e32 v108, v110, v110
	v_add_f32_e32 v108, v109, v108
	v_mul_f32_e32 v109, v107, v107
	v_fmac_f32_e32 v109, v106, v106
	v_add_f32_e32 v108, v109, v108
	v_mul_f32_e32 v109, v119, v119
	v_fmac_f32_e32 v109, v118, v118
	v_cvt_pk_bf16_f32 v105, v110, v111
	v_add_f32_e32 v116, v109, v108
	s_waitcnt vmcnt(6)
	v_lshlrev_b32_e32 v108, 16, v144
	v_and_b32_e32 v109, 0xffff0000, v144
	v_lshlrev_b32_e32 v110, 16, v145
	v_and_b32_e32 v111, 0xffff0000, v145
	v_pk_add_f32 v[102:103], v[102:103], v[110:111]
	v_pk_add_f32 v[100:101], v[100:101], v[108:109]
	v_lshlrev_b32_e32 v108, 16, v146
	v_and_b32_e32 v109, 0xffff0000, v146
	v_pk_add_f32 v[108:109], v[96:97], v[108:109]
	v_mul_f32_e32 v96, v101, v101
	v_mul_f32_e32 v97, v103, v103
	v_fmac_f32_e32 v96, v100, v100
	v_fmac_f32_e32 v97, v102, v102
	v_lshlrev_b32_e32 v110, 16, v147
	v_and_b32_e32 v111, 0xffff0000, v147
	v_add_f32_e32 v96, v96, v97
	v_mul_f32_e32 v97, v109, v109
	v_pk_add_f32 v[110:111], v[98:99], v[110:111]
	v_fmac_f32_e32 v97, v108, v108
	v_add_f32_e32 v96, v97, v96
	v_mul_f32_e32 v97, v111, v111
	v_fmac_f32_e32 v97, v110, v110
	v_add_f32_e32 v96, v97, v96
	v_add_f32_e32 v96, v116, v96
	ds_bpermute_b32 v97, v184, v96
	s_mov_b64 s[24:25], 0x8000
	s_waitcnt lgkmcnt(1)
	v_lshl_add_u64 v[112:113], v[166:167], 0, s[24:25]
	s_mov_b64 s[24:25], 0x8100
	v_lshl_add_u64 v[114:115], v[166:167], 0, s[24:25]
	s_waitcnt lgkmcnt(0)
	v_add_f32_e32 v96, v96, v97
	ds_bpermute_b32 v97, v185, v96
	v_cvt_pk_bf16_f32 v106, v106, v107
	v_cvt_pk_bf16_f32 v107, v118, v119
	v_cvt_pk_bf16_f32 v98, v100, v101
	v_cvt_pk_bf16_f32 v99, v102, v103
	v_cvt_pk_bf16_f32 v100, v108, v109
	v_cvt_pk_bf16_f32 v101, v110, v111
	global_store_dwordx4 v[112:113], v[104:107], off
	global_store_dwordx4 v[114:115], v[98:101], off
	s_and_saveexec_b64 s[24:25], s[4:5]
	s_cbranch_execz .LBB0_1963
	s_waitcnt lgkmcnt(0)
	v_add_f32_e32 v96, v96, v97
	v_mov_b32_e32 v241, v96
; __device__ __forceinline__ unsigned pk2(float lo, float hi) { f32x2 v = {lo, hi}; bf16x2_t b = __builtin_convertvector(v, bf16x2_t); return __builtin_bit_cast(unsigned, b); }
; __device__ __forceinline__ float bflo(unsigned w) { return __uint_as_float(w << 16); }
;     __device__ __forceinline__ void operator()(const f32x4 (&acc)[2][2][4][2], const Unit& u, int wr, int wc, int fr_, int fq_) const {
;     ...
;             for (int mi = 0; mi < MB; ++mi) {
;                 const int m = mb0 + mi;
;                 const size_t ro = (size_t)(ai * 128 + m * 16) * DM;
;                 const float rs = (MODE == 1) ? __builtin_amdgcn_rsqf(rsv[ai * 4 + m] * (1.0f / 1024.0f) + EPS) : 0.f; float ss = 0.f;
; #pragma unroll
;                 for (int bj = 0; bj < 2; ++bj) {
;                     const u32x4 xq = xw[mi][bj];
;                     f32x4 a0 = acc[ai][bj][m][0], a1 = acc[ai][bj][m][1];
;                     if (MODE == 1) {
;                         const u32x4 uu = uw[mi][bj];
;                         a0[0] = sigm_f(a0[0] * rs) * bflo(uu.x); a0[1] = sigm_f(a0[1] * rs) * bfhi(uu.x); a0[2] = sigm_f(a0[2] * rs) * bflo(uu.y); a0[3] = sigm_f(a0[3] * rs) * bfhi(uu.y);
;                         a1[0] = sigm_f(a1[0] * rs) * bflo(uu.z); a1[1] = sigm_f(a1[1] * rs) * bfhi(uu.z); a1[2] = sigm_f(a1[2] * rs) * bflo(uu.w); a1[3] = sigm_f(a1[3] * rs) * bfhi(uu.w);
;                     } else { a0 = a0 * scale; a1 = a1 * scale; }
;                     const f32x4 v0 = (f32x4){bflo(xq.x), bfhi(xq.x), bflo(xq.y), bfhi(xq.y)} + a0, v1 = (f32x4){bflo(xq.z), bfhi(xq.z), bflo(xq.w), bfhi(xq.w)} + a1;
;                     if (yout) { *(GAS f32x4*)(yp + ro + bj * 128) = v0; *(GAS f32x4*)(yp + ro + bj * 128 + 4) = v1; }
;                     else {
;                         u32x4 w; w.x = pk2(v0[0], v0[1]); w.y = pk2(v0[2], v0[3]); w.z = pk2(v1[0], v1[1]); w.w = pk2(v1[2], v1[3]);
;                         *(GAS u32x4*)(xop + ro + bj * 128) = w;
;                         ss += (v0[0] * v0[0] + v0[1] * v0[1]) + (v0[2] * v0[2] + v0[3] * v0[3]) + (v1[0] * v1[0] + v1[1] * v1[1]) + (v1[2] * v1[2] + v1[3] * v1[3]);
;                     }
;                 }
;                 if (!yout) { ss += __shfl_xor(ss, 16); ss += __shfl_xor(ss, 32);
;                     if (fq == 0) __hip_atomic_fetch_add(sn + ai * 128 + m * 16, ss, __ATOMIC_RELAXED, __HIP_MEMORY_SCOPE_AGENT); }
.LBB0_1963:
	s_or_b64 exec, exec, s[24:25]
	s_waitcnt vmcnt(7)
	v_lshlrev_b32_e32 v100, 16, v140
	v_and_b32_e32 v101, 0xffff0000, v140
	v_lshlrev_b32_e32 v102, 16, v141
	v_and_b32_e32 v103, 0xffff0000, v141
	v_pk_add_f32 v[94:95], v[94:95], v[102:103]
	v_pk_add_f32 v[92:93], v[92:93], v[100:101]
	v_lshlrev_b32_e32 v100, 16, v142
	v_and_b32_e32 v101, 0xffff0000, v142
	v_lshlrev_b32_e32 v102, 16, v143
	v_and_b32_e32 v103, 0xffff0000, v143
	v_pk_add_f32 v[102:103], v[90:91], v[102:103]
	v_pk_add_f32 v[90:91], v[88:89], v[100:101]
	v_cvt_pk_bf16_f32 v88, v92, v93
	v_mul_f32_e32 v93, v93, v93
	v_fmac_f32_e32 v93, v92, v92
	v_mul_f32_e32 v92, v95, v95
	v_fmac_f32_e32 v92, v94, v94
	v_add_f32_e32 v92, v93, v92
	v_mul_f32_e32 v93, v91, v91
	v_fmac_f32_e32 v93, v90, v90
	v_add_f32_e32 v92, v93, v92
	v_mul_f32_e32 v93, v103, v103
	v_fmac_f32_e32 v93, v102, v102
	v_cvt_pk_bf16_f32 v89, v94, v95
	v_add_f32_e32 v100, v93, v92
	s_waitcnt vmcnt(6)
	v_lshlrev_b32_e32 v92, 16, v136
	v_and_b32_e32 v93, 0xffff0000, v136
	v_lshlrev_b32_e32 v94, 16, v137
	v_and_b32_e32 v95, 0xffff0000, v137
	v_pk_add_f32 v[86:87], v[86:87], v[94:95]
	v_pk_add_f32 v[84:85], v[84:85], v[92:93]
	v_lshlrev_b32_e32 v92, 16, v138
	v_and_b32_e32 v93, 0xffff0000, v138
	v_pk_add_f32 v[92:93], v[80:81], v[92:93]
	v_mul_f32_e32 v80, v85, v85
	v_mul_f32_e32 v81, v87, v87
	v_fmac_f32_e32 v80, v84, v84
	v_fmac_f32_e32 v81, v86, v86
	v_lshlrev_b32_e32 v94, 16, v139
	v_and_b32_e32 v95, 0xffff0000, v139
	v_add_f32_e32 v80, v80, v81
	v_mul_f32_e32 v81, v93, v93
	v_pk_add_f32 v[94:95], v[82:83], v[94:95]
	v_fmac_f32_e32 v81, v92, v92
	v_add_f32_e32 v80, v81, v80
	v_mul_f32_e32 v81, v95, v95
	v_fmac_f32_e32 v81, v94, v94
	v_add_f32_e32 v80, v81, v80
	v_add_f32_e32 v80, v100, v80
	ds_bpermute_b32 v81, v184, v80
	s_mov_b64 s[24:25], 0x10000
	s_waitcnt lgkmcnt(1)
	v_lshl_add_u64 v[96:97], v[166:167], 0, s[24:25]
	s_mov_b64 s[24:25], 0x10100
	v_lshl_add_u64 v[98:99], v[166:167], 0, s[24:25]
	s_waitcnt lgkmcnt(0)
	v_add_f32_e32 v80, v80, v81
	ds_bpermute_b32 v81, v185, v80
	v_cvt_pk_bf16_f32 v90, v90, v91
	v_cvt_pk_bf16_f32 v91, v102, v103
	v_cvt_pk_bf16_f32 v82, v84, v85
	v_cvt_pk_bf16_f32 v83, v86, v87
	v_cvt_pk_bf16_f32 v84, v92, v93
	v_cvt_pk_bf16_f32 v85, v94, v95
	global_store_dwordx4 v[96:97], v[88:91], off
	global_store_dwordx4 v[98:99], v[82:85], off
	s_and_saveexec_b64 s[24:25], s[4:5]
	s_cbranch_execz .LBB0_1965
	s_waitcnt lgkmcnt(0)
	v_add_f32_e32 v80, v80, v81
	v_mov_b32_e32 v242, v80
.LBB0_1965:
	s_or_b64 exec, exec, s[24:25]
	s_waitcnt vmcnt(7)
	v_lshlrev_b32_e32 v84, 16, v132
	v_and_b32_e32 v85, 0xffff0000, v132
	v_lshlrev_b32_e32 v86, 16, v133
	v_and_b32_e32 v87, 0xffff0000, v133
	v_pk_add_f32 v[78:79], v[78:79], v[86:87]
	v_pk_add_f32 v[76:77], v[76:77], v[84:85]
	v_lshlrev_b32_e32 v84, 16, v134
	v_and_b32_e32 v85, 0xffff0000, v134
	v_lshlrev_b32_e32 v86, 16, v135
	v_and_b32_e32 v87, 0xffff0000, v135
	v_pk_add_f32 v[86:87], v[74:75], v[86:87]
	v_pk_add_f32 v[74:75], v[72:73], v[84:85]
	v_cvt_pk_bf16_f32 v72, v76, v77
	v_mul_f32_e32 v77, v77, v77
	v_fmac_f32_e32 v77, v76, v76
	v_mul_f32_e32 v76, v79, v79
	v_fmac_f32_e32 v76, v78, v78
	v_add_f32_e32 v76, v77, v76
	v_mul_f32_e32 v77, v75, v75
	v_fmac_f32_e32 v77, v74, v74
	v_add_f32_e32 v76, v77, v76
	v_mul_f32_e32 v77, v87, v87
	v_fmac_f32_e32 v77, v86, v86
	v_cvt_pk_bf16_f32 v73, v78, v79
	v_add_f32_e32 v84, v77, v76
	s_waitcnt vmcnt(6)
	v_lshlrev_b32_e32 v76, 16, v128
	v_and_b32_e32 v77, 0xffff0000, v128
	v_lshlrev_b32_e32 v78, 16, v129
	v_and_b32_e32 v79, 0xffff0000, v129
	v_pk_add_f32 v[70:71], v[70:71], v[78:79]
	v_pk_add_f32 v[68:69], v[68:69], v[76:77]
	v_lshlrev_b32_e32 v76, 16, v130
	v_and_b32_e32 v77, 0xffff0000, v130
	v_pk_add_f32 v[76:77], v[64:65], v[76:77]
	v_mul_f32_e32 v64, v69, v69
	v_mul_f32_e32 v65, v71, v71
	v_fmac_f32_e32 v64, v68, v68
	v_fmac_f32_e32 v65, v70, v70
	v_lshlrev_b32_e32 v78, 16, v131
	v_and_b32_e32 v79, 0xffff0000, v131
	v_add_f32_e32 v64, v64, v65
	v_mul_f32_e32 v65, v77, v77
	v_pk_add_f32 v[78:79], v[66:67], v[78:79]
	v_fmac_f32_e32 v65, v76, v76
	v_add_f32_e32 v64, v65, v64
	v_mul_f32_e32 v65, v79, v79
	v_fmac_f32_e32 v65, v78, v78
	v_add_f32_e32 v64, v65, v64
	v_add_f32_e32 v64, v84, v64
	ds_bpermute_b32 v65, v184, v64
	s_mov_b64 s[24:25], 0x18000
	s_waitcnt lgkmcnt(1)
	v_lshl_add_u64 v[80:81], v[166:167], 0, s[24:25]
	s_mov_b64 s[24:25], 0x18100
	v_lshl_add_u64 v[82:83], v[166:167], 0, s[24:25]
	s_waitcnt lgkmcnt(0)
	v_add_f32_e32 v64, v64, v65
	ds_bpermute_b32 v65, v185, v64
	v_cvt_pk_bf16_f32 v74, v74, v75
	v_cvt_pk_bf16_f32 v75, v86, v87
	v_cvt_pk_bf16_f32 v66, v68, v69
	v_cvt_pk_bf16_f32 v67, v70, v71
	v_cvt_pk_bf16_f32 v68, v76, v77
	v_cvt_pk_bf16_f32 v69, v78, v79
	global_store_dwordx4 v[80:81], v[72:75], off
	global_store_dwordx4 v[82:83], v[66:69], off
	s_and_saveexec_b64 s[24:25], s[4:5]
	s_cbranch_execz .LBB0_1967
	s_waitcnt lgkmcnt(0)
	v_add_f32_e32 v64, v64, v65
	v_mov_b32_e32 v243, v64

; __device__ __forceinline__ unsigned pk2(float lo, float hi) { f32x2 v = {lo, hi}; bf16x2_t b = __builtin_convertvector(v, bf16x2_t); return __builtin_bit_cast(unsigned, b); }
; __device__ __forceinline__ float bflo(unsigned w) { return __uint_as_float(w << 16); }
;     __device__ __forceinline__ void operator()(const f32x4 (&acc)[2][2][4][2], const Unit& u, int wr, int wc, int fr_, int fq_) const {
;     ...
;             for (int mi = 0; mi < MB; ++mi) {
;                 const int m = mb0 + mi;
;                 const size_t ro = (size_t)(ai * 128 + m * 16) * DM;
;                 const float rs = (MODE == 1) ? __builtin_amdgcn_rsqf(rsv[ai * 4 + m] * (1.0f / 1024.0f) + EPS) : 0.f; float ss = 0.f;
; #pragma unroll
;                 for (int bj = 0; bj < 2; ++bj) {
;                     const u32x4 xq = xw[mi][bj];
;                     f32x4 a0 = acc[ai][bj][m][0], a1 = acc[ai][bj][m][1];
;                     if (MODE == 1) {
;                         const u32x4 uu = uw[mi][bj];
;                         a0[0] = sigm_f(a0[0] * rs) * bflo(uu.x); a0[1] = sigm_f(a0[1] * rs) * bfhi(uu.x); a0[2] = sigm_f(a0[2] * rs) * bflo(uu.y); a0[3] = sigm_f(a0[3] * rs) * bfhi(uu.y);
;                         a1[0] = sigm_f(a1[0] * rs) * bflo(uu.z); a1[1] = sigm_f(a1[1] * rs) * bfhi(uu.z); a1[2] = sigm_f(a1[2] * rs) * bflo(uu.w); a1[3] = sigm_f(a1[3] * rs) * bfhi(uu.w);
;                     } else { a0 = a0 * scale; a1 = a1 * scale; }
;                     const f32x4 v0 = (f32x4){bflo(xq.x), bfhi(xq.x), bflo(xq.y), bfhi(xq.y)} + a0, v1 = (f32x4){bflo(xq.z), bfhi(xq.z), bflo(xq.w), bfhi(xq.w)} + a1;
;                     if (yout) { *(GAS f32x4*)(yp + ro + bj * 128) = v0; *(GAS f32x4*)(yp + ro + bj * 128 + 4) = v1; }
;                     else {
;                         u32x4 w; w.x = pk2(v0[0], v0[1]); w.y = pk2(v0[2], v0[3]); w.z = pk2(v1[0], v1[1]); w.w = pk2(v1[2], v1[3]);
;                         *(GAS u32x4*)(xop + ro + bj * 128) = w;
;                         ss += (v0[0] * v0[0] + v0[1] * v0[1]) + (v0[2] * v0[2] + v0[3] * v0[3]) + (v1[0] * v1[0] + v1[1] * v1[1]) + (v1[2] * v1[2] + v1[3] * v1[3]);
;                     }
;                 }
;                 if (!yout) { ss += __shfl_xor(ss, 16); ss += __shfl_xor(ss, 32);
;                     if (fq == 0) __hip_atomic_fetch_add(sn + ai * 128 + m * 16, ss, __ATOMIC_RELAXED, __HIP_MEMORY_SCOPE_AGENT); }
.LBB0_1973:
	s_or_b64 exec, exec, s[24:25]
	s_waitcnt vmcnt(7)
	v_lshlrev_b32_e32 v20, 16, v68
	v_and_b32_e32 v21, 0xffff0000, v68
	v_lshlrev_b32_e32 v22, 16, v69
	v_and_b32_e32 v23, 0xffff0000, v69
	v_pk_add_f32 v[14:15], v[14:15], v[22:23]
	v_pk_add_f32 v[12:13], v[12:13], v[20:21]
	v_lshlrev_b32_e32 v20, 16, v70
	v_and_b32_e32 v21, 0xffff0000, v70
	v_lshlrev_b32_e32 v22, 16, v71
	v_and_b32_e32 v23, 0xffff0000, v71
	v_pk_add_f32 v[22:23], v[10:11], v[22:23]
	v_pk_add_f32 v[10:11], v[8:9], v[20:21]
	v_cvt_pk_bf16_f32 v8, v12, v13
	v_mul_f32_e32 v13, v13, v13
	v_fmac_f32_e32 v13, v12, v12
	v_mul_f32_e32 v12, v15, v15
	v_fmac_f32_e32 v12, v14, v14
	v_add_f32_e32 v12, v13, v12
	v_mul_f32_e32 v13, v11, v11
	v_fmac_f32_e32 v13, v10, v10
	v_add_f32_e32 v12, v13, v12
	v_mul_f32_e32 v13, v23, v23
	v_fmac_f32_e32 v13, v22, v22
	v_cvt_pk_bf16_f32 v9, v14, v15
	v_add_f32_e32 v20, v13, v12
	s_waitcnt vmcnt(6)
	s_and_saveexec_b64 s[24:25], s[4:5]
	global_atomic_add_f32 v[164:165], v240, off
	global_atomic_add_f32 v[164:165], v241, off offset:64
	global_atomic_add_f32 v[164:165], v242, off offset:128
	global_atomic_add_f32 v[164:165], v243, off offset:192
	s_or_b64 exec, exec, s[24:25]
	v_lshlrev_b32_e32 v12, 16, v64
	v_and_b32_e32 v13, 0xffff0000, v64
	v_lshlrev_b32_e32 v14, 16, v65
	v_and_b32_e32 v15, 0xffff0000, v65
	v_pk_add_f32 v[6:7], v[6:7], v[14:15]
	v_pk_add_f32 v[4:5], v[4:5], v[12:13]
	v_lshlrev_b32_e32 v12, 16, v66
	v_and_b32_e32 v13, 0xffff0000, v66
	v_pk_add_f32 v[12:13], v[0:1], v[12:13]
	v_mul_f32_e32 v0, v5, v5
	v_mul_f32_e32 v1, v7, v7
	v_fmac_f32_e32 v0, v4, v4
	v_fmac_f32_e32 v1, v6, v6
	v_lshlrev_b32_e32 v14, 16, v67
	v_and_b32_e32 v15, 0xffff0000, v67
	v_add_f32_e32 v0, v0, v1
	v_mul_f32_e32 v1, v13, v13
	v_pk_add_f32 v[14:15], v[2:3], v[14:15]
	v_fmac_f32_e32 v1, v12, v12
	v_add_f32_e32 v0, v1, v0
	v_mul_f32_e32 v1, v15, v15
	v_fmac_f32_e32 v1, v14, v14
	v_add_f32_e32 v0, v1, v0
	v_add_f32_e32 v0, v20, v0
	ds_bpermute_b32 v1, v184, v0
	s_mov_b64 s[24:25], 0x58000
	s_waitcnt lgkmcnt(1)
	v_lshl_add_u64 v[16:17], v[166:167], 0, s[24:25]
	s_mov_b64 s[24:25], 0x58100
	v_lshl_add_u64 v[18:19], v[166:167], 0, s[24:25]
	s_waitcnt lgkmcnt(0)
	v_add_f32_e32 v0, v0, v1
	ds_bpermute_b32 v1, v185, v0
	v_cvt_pk_bf16_f32 v10, v10, v11
	v_cvt_pk_bf16_f32 v11, v22, v23
	v_cvt_pk_bf16_f32 v2, v4, v5
	v_cvt_pk_bf16_f32 v3, v6, v7
	v_cvt_pk_bf16_f32 v4, v12, v13
	v_cvt_pk_bf16_f32 v5, v14, v15
	global_store_dwordx4 v[16:17], v[8:11], off
	global_store_dwordx4 v[18:19], v[2:5], off
	s_and_saveexec_b64 s[24:25], s[4:5]
	s_cbranch_execz .LBB0_1975
	s_waitcnt lgkmcnt(0)
	v_add_f32_e32 v0, v0, v1
	global_atomic_add_f32 v[164:165], v0, off offset:704

; __device__ __forceinline__ float bflo(unsigned w) { return __uint_as_float(w << 16); }
; #define GAS __attribute__((address_space(1)))
;     __device__ __forceinline__ void operator()(const f32x4 (&acc)[2][2][4][2], const Unit& u, int wr, int wc, int fr_, int fq_) const {
;     ...
; #pragma unroll
;         for (int ab = 0; ab < 8 / MB; ++ab) {
;             const int ai = (ab * MB) >> 2, mb0 = (ab * MB) & 3;
;             u32x4 xw[MB][2], uw[MB][2];
; #pragma unroll
;             for (int mi = 0; mi < MB; ++mi)
; #pragma unroll
;                 for (int bj = 0; bj < 2; ++bj) { xw[mi][bj] = *(const GAS u32x4*)(xip + (size_t)(ai * 128 + (mb0 + mi) * 16) * DM + bj * 128);
;                     if (MODE == 1) uw[mi][bj] = *(const GAS u32x4*)(up + (size_t)(ai * 128 + (mb0 + mi) * 16) * DM + bj * 128); }
; #pragma unroll
;             for (int mi = 0; mi < MB; ++mi) {
;                 const int m = mb0 + mi;
;                 const size_t ro = (size_t)(ai * 128 + m * 16) * DM;
;                 const float rs = (MODE == 1) ? __builtin_amdgcn_rsqf(rsv[ai * 4 + m] * (1.0f / 1024.0f) + EPS) : 0.f; float ss = 0.f;
; #pragma unroll
;                 for (int bj = 0; bj < 2; ++bj) {
;                     const u32x4 xq = xw[mi][bj];
;                     f32x4 a0 = acc[ai][bj][m][0], a1 = acc[ai][bj][m][1];
;                     if (MODE == 1) {
;                         const u32x4 uu = uw[mi][bj];
;                         a0[0] = sigm_f(a0[0] * rs) * bflo(uu.x); a0[1] = sigm_f(a0[1] * rs) * bfhi(uu.x); a0[2] = sigm_f(a0[2] * rs) * bflo(uu.y); a0[3] = sigm_f(a0[3] * rs) * bfhi(uu.y);
;                         a1[0] = sigm_f(a1[0] * rs) * bflo(uu.z); a1[1] = sigm_f(a1[1] * rs) * bfhi(uu.z); a1[2] = sigm_f(a1[2] * rs) * bflo(uu.w); a1[3] = sigm_f(a1[3] * rs) * bfhi(uu.w);
;                     } else { a0 = a0 * scale; a1 = a1 * scale; }
;                     const f32x4 v0 = (f32x4){bflo(xq.x), bfhi(xq.x), bflo(xq.y), bfhi(xq.y)} + a0, v1 = (f32x4){bflo(xq.z), bfhi(xq.z), bflo(xq.w), bfhi(xq.w)} + a1;
;                     if (yout) { *(GAS f32x4*)(yp + ro + bj * 128) = v0; *(GAS f32x4*)(yp + ro + bj * 128 + 4) = v1; }
;                     else {
;                         u32x4 w; w.x = pk2(v0[0], v0[1]); w.y = pk2(v0[2], v0[3]); w.z = pk2(v1[0], v1[1]); w.w = pk2(v1[2], v1[3]);
;                         *(GAS u32x4*)(xop + ro + bj * 128) = w;
.LBB0_2183:
	s_lshl_b32 s6, s64, 8
	v_mov_b32_e32 v180, v182
	s_add_i32 s6, s6, s53
	s_nop 0
	v_and_or_b32 v164, v180, 15, s6
	s_lshl_b32 s6, s63, 8
	v_ashrrev_i32_e32 v128, 1, v180
	s_or_b32 s6, s6, s54
	v_and_b32_e32 v128, -8, v128
	v_ashrrev_i32_e32 v165, 31, v164
	v_add_u32_e32 v128, s6, v128
	v_lshlrev_b64 v[130:131], 11, v[164:165]
	v_ashrrev_i32_e32 v129, 31, v128
	v_lshl_add_u64 v[130:131], s[10:11], 0, v[130:131]
	v_lshl_add_u64 v[166:167], v[128:129], 1, v[130:131]
	global_load_dwordx4 v[170:173], v[166:167], off
	global_load_dwordx4 v[174:177], v[166:167], off offset:256
	v_add_co_u32_e32 v128, vcc, s70, v166
	v_cmp_gt_u32_e64 s[6:7], 16, v180
	s_nop 0
	v_addc_co_u32_e32 v129, vcc, 0, v167, vcc
	v_add_co_u32_e32 v130, vcc, s37, v166
	v_lshl_add_u64 v[164:165], v[164:165], 2, s[12:13]
	s_nop 0
	v_addc_co_u32_e32 v131, vcc, 0, v167, vcc
	v_add_co_u32_e32 v178, vcc, s59, v166
	s_waitcnt vmcnt(0)
	v_lshlrev_b32_e32 v180, 16, v172
	v_addc_co_u32_e32 v179, vcc, 0, v167, vcc
	global_load_dwordx4 v[148:151], v[128:129], off
	global_load_dwordx4 v[144:147], v[128:129], off offset:256
	global_load_dwordx4 v[140:143], v[130:131], off
	global_load_dwordx4 v[136:139], v[130:131], off offset:256
	global_load_dwordx4 v[132:135], v[178:179], off
	s_nop 0
	global_load_dwordx4 v[128:131], v[178:179], off offset:256
	v_lshlrev_b32_e32 v178, 16, v170
	v_and_b32_e32 v179, 0xffff0000, v170
	v_lshlrev_b32_e32 v170, 16, v171
	v_and_b32_e32 v171, 0xffff0000, v171
	v_lshlrev_b32_e32 v204, 16, v174
	v_and_b32_e32 v205, 0xffff0000, v174
	v_lshlrev_b32_e32 v174, 16, v175
	v_and_b32_e32 v175, 0xffff0000, v175
	v_and_b32_e32 v181, 0xffff0000, v172
	v_lshlrev_b32_e32 v172, 16, v173
	v_and_b32_e32 v173, 0xffff0000, v173
	v_lshlrev_b32_e32 v206, 16, v176
	v_and_b32_e32 v207, 0xffff0000, v176
	v_lshlrev_b32_e32 v176, 16, v177
	v_and_b32_e32 v177, 0xffff0000, v177
	v_pk_fma_f32 v[126:127], v[126:127], 0.5, v[170:171] op_sel_hi:[1,0,1]
	v_pk_fma_f32 v[124:125], v[124:125], 0.5, v[178:179] op_sel_hi:[1,0,1]
	v_pk_fma_f32 v[118:119], v[118:119], 0.5, v[174:175] op_sel_hi:[1,0,1]
	v_pk_fma_f32 v[116:117], v[116:117], 0.5, v[204:205] op_sel_hi:[1,0,1]
	v_pk_fma_f32 v[122:123], v[122:123], 0.5, v[172:173] op_sel_hi:[1,0,1]
	v_pk_fma_f32 v[120:121], v[120:121], 0.5, v[180:181] op_sel_hi:[1,0,1]
	v_pk_fma_f32 v[170:171], v[114:115], 0.5, v[176:177] op_sel_hi:[1,0,1]
	v_pk_fma_f32 v[172:173], v[112:113], 0.5, v[206:207] op_sel_hi:[1,0,1]
	v_mul_f32_e32 v114, v125, v125
	v_mul_f32_e32 v115, v127, v127
	v_mul_f32_e32 v174, v117, v117
	v_mul_f32_e32 v175, v119, v119
	v_cvt_pk_bf16_f32 v112, v124, v125
	v_mul_f32_e32 v125, v121, v121
	v_mul_f32_e32 v176, v173, v173
	v_fmac_f32_e32 v114, v124, v124
	v_fmac_f32_e32 v115, v126, v126
	v_fmac_f32_e32 v174, v116, v116
	v_fmac_f32_e32 v175, v118, v118
	v_cvt_pk_bf16_f32 v113, v126, v127
	v_mul_f32_e32 v127, v123, v123
	v_mul_f32_e32 v177, v171, v171
	v_fmac_f32_e32 v125, v120, v120
	v_fmac_f32_e32 v176, v172, v172
	v_add_f32_e32 v114, v114, v115
	v_add_f32_e32 v115, v174, v175
	v_fmac_f32_e32 v127, v122, v122
	v_fmac_f32_e32 v177, v170, v170
	v_add_f32_e32 v114, v125, v114
	v_add_f32_e32 v115, v176, v115
	v_add_f32_e32 v114, v127, v114
	v_add_f32_e32 v115, v177, v115
	v_add_f32_e32 v124, v114, v115
	ds_bpermute_b32 v125, v184, v124
	v_cvt_pk_bf16_f32 v114, v120, v121
	v_cvt_pk_bf16_f32 v115, v122, v123
	global_store_dwordx4 v[166:167], v[112:115], off
	s_waitcnt lgkmcnt(0)
	s_nop 0
	v_add_f32_e32 v112, v124, v125
	ds_bpermute_b32 v113, v185, v112
	v_cvt_pk_bf16_f32 v114, v116, v117
	v_cvt_pk_bf16_f32 v115, v118, v119
	v_cvt_pk_bf16_f32 v116, v172, v173
	v_cvt_pk_bf16_f32 v117, v170, v171
	global_store_dwordx4 v[166:167], v[114:117], off offset:256
	s_and_saveexec_b64 s[24:25], s[6:7]
	s_cbranch_execz .LBB0_2185
	s_waitcnt lgkmcnt(0)
	v_add_f32_e32 v112, v112, v113
	v_mov_b32_e32 v240, v112
.LBB0_2185:
	s_or_b64 exec, exec, s[24:25]
	s_waitcnt vmcnt(7)
	v_lshlrev_b32_e32 v116, 16, v148
	v_and_b32_e32 v117, 0xffff0000, v148
	v_lshlrev_b32_e32 v118, 16, v149
	v_and_b32_e32 v119, 0xffff0000, v149
	v_pk_fma_f32 v[110:111], v[110:111], 0.5, v[118:119] op_sel_hi:[1,0,1]
	v_pk_fma_f32 v[108:109], v[108:109], 0.5, v[116:117] op_sel_hi:[1,0,1]
	v_lshlrev_b32_e32 v116, 16, v150
	v_and_b32_e32 v117, 0xffff0000, v150
	v_lshlrev_b32_e32 v118, 16, v151
	v_and_b32_e32 v119, 0xffff0000, v151
	v_pk_fma_f32 v[118:119], v[106:107], 0.5, v[118:119] op_sel_hi:[1,0,1]
	v_pk_fma_f32 v[106:107], v[104:105], 0.5, v[116:117] op_sel_hi:[1,0,1]
	v_cvt_pk_bf16_f32 v104, v108, v109
	v_mul_f32_e32 v109, v109, v109
	v_fmac_f32_e32 v109, v108, v108
	v_mul_f32_e32 v108, v111, v111
	v_fmac_f32_e32 v108, v110, v110
	v_add_f32_e32 v108, v109, v108
	v_mul_f32_e32 v109, v107, v107
	v_fmac_f32_e32 v109, v106, v106
	v_add_f32_e32 v108, v109, v108
	v_mul_f32_e32 v109, v119, v119
	v_fmac_f32_e32 v109, v118, v118
	v_cvt_pk_bf16_f32 v105, v110, v111
	v_add_f32_e32 v116, v109, v108
	s_waitcnt vmcnt(6)
	v_lshlrev_b32_e32 v108, 16, v144
	v_and_b32_e32 v109, 0xffff0000, v144
	v_lshlrev_b32_e32 v110, 16, v145
	v_and_b32_e32 v111, 0xffff0000, v145
	v_pk_fma_f32 v[102:103], v[102:103], 0.5, v[110:111] op_sel_hi:[1,0,1]
	v_pk_fma_f32 v[100:101], v[100:101], 0.5, v[108:109] op_sel_hi:[1,0,1]
	v_lshlrev_b32_e32 v108, 16, v146
	v_and_b32_e32 v109, 0xffff0000, v146
	v_pk_fma_f32 v[108:109], v[96:97], 0.5, v[108:109] op_sel_hi:[1,0,1]
	v_mul_f32_e32 v96, v101, v101
	v_mul_f32_e32 v97, v103, v103
	v_fmac_f32_e32 v96, v100, v100
	v_fmac_f32_e32 v97, v102, v102
	v_lshlrev_b32_e32 v110, 16, v147
	v_and_b32_e32 v111, 0xffff0000, v147
	v_add_f32_e32 v96, v96, v97
	v_mul_f32_e32 v97, v109, v109
	v_pk_fma_f32 v[110:111], v[98:99], 0.5, v[110:111] op_sel_hi:[1,0,1]
	v_fmac_f32_e32 v97, v108, v108
	v_add_f32_e32 v96, v97, v96
	v_mul_f32_e32 v97, v111, v111
	v_fmac_f32_e32 v97, v110, v110
	v_add_f32_e32 v96, v97, v96
	v_add_f32_e32 v96, v116, v96
	ds_bpermute_b32 v97, v184, v96
	s_mov_b64 s[24:25], 0x8000
	s_waitcnt lgkmcnt(1)
	v_lshl_add_u64 v[112:113], v[166:167], 0, s[24:25]
	s_mov_b64 s[24:25], 0x8100
	v_lshl_add_u64 v[114:115], v[166:167], 0, s[24:25]
	s_waitcnt lgkmcnt(0)
	v_add_f32_e32 v96, v96, v97
	ds_bpermute_b32 v97, v185, v96
	v_cvt_pk_bf16_f32 v106, v106, v107
	v_cvt_pk_bf16_f32 v107, v118, v119
	v_cvt_pk_bf16_f32 v98, v100, v101
	v_cvt_pk_bf16_f32 v99, v102, v103
	v_cvt_pk_bf16_f32 v100, v108, v109
	v_cvt_pk_bf16_f32 v101, v110, v111
	global_store_dwordx4 v[112:113], v[104:107], off
	global_store_dwordx4 v[114:115], v[98:101], off
	s_and_saveexec_b64 s[24:25], s[6:7]
	s_cbranch_execz .LBB0_2187
	s_waitcnt lgkmcnt(0)
	v_add_f32_e32 v96, v96, v97
	v_mov_b32_e32 v241, v96
; __device__ __forceinline__ unsigned pk2(float lo, float hi) { f32x2 v = {lo, hi}; bf16x2_t b = __builtin_convertvector(v, bf16x2_t); return __builtin_bit_cast(unsigned, b); }
; __device__ __forceinline__ float bflo(unsigned w) { return __uint_as_float(w << 16); }
;     __device__ __forceinline__ void operator()(const f32x4 (&acc)[2][2][4][2], const Unit& u, int wr, int wc, int fr_, int fq_) const {
;     ...
;             for (int mi = 0; mi < MB; ++mi) {
;                 const int m = mb0 + mi;
;                 const size_t ro = (size_t)(ai * 128 + m * 16) * DM;
;                 const float rs = (MODE == 1) ? __builtin_amdgcn_rsqf(rsv[ai * 4 + m] * (1.0f / 1024.0f) + EPS) : 0.f; float ss = 0.f;
; #pragma unroll
;                 for (int bj = 0; bj < 2; ++bj) {
;                     const u32x4 xq = xw[mi][bj];
;                     f32x4 a0 = acc[ai][bj][m][0], a1 = acc[ai][bj][m][1];
;                     if (MODE == 1) {
;                         const u32x4 uu = uw[mi][bj];
;                         a0[0] = sigm_f(a0[0] * rs) * bflo(uu.x); a0[1] = sigm_f(a0[1] * rs) * bfhi(uu.x); a0[2] = sigm_f(a0[2] * rs) * bflo(uu.y); a0[3] = sigm_f(a0[3] * rs) * bfhi(uu.y);
;                         a1[0] = sigm_f(a1[0] * rs) * bflo(uu.z); a1[1] = sigm_f(a1[1] * rs) * bfhi(uu.z); a1[2] = sigm_f(a1[2] * rs) * bflo(uu.w); a1[3] = sigm_f(a1[3] * rs) * bfhi(uu.w);
;                     } else { a0 = a0 * scale; a1 = a1 * scale; }
;                     const f32x4 v0 = (f32x4){bflo(xq.x), bfhi(xq.x), bflo(xq.y), bfhi(xq.y)} + a0, v1 = (f32x4){bflo(xq.z), bfhi(xq.z), bflo(xq.w), bfhi(xq.w)} + a1;
;                     if (yout) { *(GAS f32x4*)(yp + ro + bj * 128) = v0; *(GAS f32x4*)(yp + ro + bj * 128 + 4) = v1; }
;                     else {
;                         u32x4 w; w.x = pk2(v0[0], v0[1]); w.y = pk2(v0[2], v0[3]); w.z = pk2(v1[0], v1[1]); w.w = pk2(v1[2], v1[3]);
;                         *(GAS u32x4*)(xop + ro + bj * 128) = w;
;                         ss += (v0[0] * v0[0] + v0[1] * v0[1]) + (v0[2] * v0[2] + v0[3] * v0[3]) + (v1[0] * v1[0] + v1[1] * v1[1]) + (v1[2] * v1[2] + v1[3] * v1[3]);
;                     }
;                 }
;                 if (!yout) { ss += __shfl_xor(ss, 16); ss += __shfl_xor(ss, 32);
;                     if (fq == 0) __hip_atomic_fetch_add(sn + ai * 128 + m * 16, ss, __ATOMIC_RELAXED, __HIP_MEMORY_SCOPE_AGENT); }
.LBB0_2187:
	s_or_b64 exec, exec, s[24:25]
	s_waitcnt vmcnt(7)
	v_lshlrev_b32_e32 v100, 16, v140
	v_and_b32_e32 v101, 0xffff0000, v140
	v_lshlrev_b32_e32 v102, 16, v141
	v_and_b32_e32 v103, 0xffff0000, v141
	v_pk_fma_f32 v[94:95], v[94:95], 0.5, v[102:103] op_sel_hi:[1,0,1]
	v_pk_fma_f32 v[92:93], v[92:93], 0.5, v[100:101] op_sel_hi:[1,0,1]
	v_lshlrev_b32_e32 v100, 16, v142
	v_and_b32_e32 v101, 0xffff0000, v142
	v_lshlrev_b32_e32 v102, 16, v143
	v_and_b32_e32 v103, 0xffff0000, v143
	v_pk_fma_f32 v[102:103], v[90:91], 0.5, v[102:103] op_sel_hi:[1,0,1]
	v_pk_fma_f32 v[90:91], v[88:89], 0.5, v[100:101] op_sel_hi:[1,0,1]
	v_cvt_pk_bf16_f32 v88, v92, v93
	v_mul_f32_e32 v93, v93, v93
	v_fmac_f32_e32 v93, v92, v92
	v_mul_f32_e32 v92, v95, v95
	v_fmac_f32_e32 v92, v94, v94
	v_add_f32_e32 v92, v93, v92
	v_mul_f32_e32 v93, v91, v91
	v_fmac_f32_e32 v93, v90, v90
	v_add_f32_e32 v92, v93, v92
	v_mul_f32_e32 v93, v103, v103
	v_fmac_f32_e32 v93, v102, v102
	v_cvt_pk_bf16_f32 v89, v94, v95
	v_add_f32_e32 v100, v93, v92
	s_waitcnt vmcnt(6)
	v_lshlrev_b32_e32 v92, 16, v136
	v_and_b32_e32 v93, 0xffff0000, v136
	v_lshlrev_b32_e32 v94, 16, v137
	v_and_b32_e32 v95, 0xffff0000, v137
	v_pk_fma_f32 v[86:87], v[86:87], 0.5, v[94:95] op_sel_hi:[1,0,1]
	v_pk_fma_f32 v[84:85], v[84:85], 0.5, v[92:93] op_sel_hi:[1,0,1]
	v_lshlrev_b32_e32 v92, 16, v138
	v_and_b32_e32 v93, 0xffff0000, v138
	v_pk_fma_f32 v[92:93], v[80:81], 0.5, v[92:93] op_sel_hi:[1,0,1]
	v_mul_f32_e32 v80, v85, v85
	v_mul_f32_e32 v81, v87, v87
	v_fmac_f32_e32 v80, v84, v84
	v_fmac_f32_e32 v81, v86, v86
	v_lshlrev_b32_e32 v94, 16, v139
	v_and_b32_e32 v95, 0xffff0000, v139
	v_add_f32_e32 v80, v80, v81
	v_mul_f32_e32 v81, v93, v93
	v_pk_fma_f32 v[94:95], v[82:83], 0.5, v[94:95] op_sel_hi:[1,0,1]
	v_fmac_f32_e32 v81, v92, v92
	v_add_f32_e32 v80, v81, v80
	v_mul_f32_e32 v81, v95, v95
	v_fmac_f32_e32 v81, v94, v94
	v_add_f32_e32 v80, v81, v80
	v_add_f32_e32 v80, v100, v80
	ds_bpermute_b32 v81, v184, v80
	s_mov_b64 s[24:25], 0x10000
	s_waitcnt lgkmcnt(1)
	v_lshl_add_u64 v[96:97], v[166:167], 0, s[24:25]
	s_mov_b64 s[24:25], 0x10100
	v_lshl_add_u64 v[98:99], v[166:167], 0, s[24:25]
	s_waitcnt lgkmcnt(0)
	v_add_f32_e32 v80, v80, v81
	ds_bpermute_b32 v81, v185, v80
	v_cvt_pk_bf16_f32 v90, v90, v91
	v_cvt_pk_bf16_f32 v91, v102, v103
	v_cvt_pk_bf16_f32 v82, v84, v85
	v_cvt_pk_bf16_f32 v83, v86, v87
	v_cvt_pk_bf16_f32 v84, v92, v93
	v_cvt_pk_bf16_f32 v85, v94, v95
	global_store_dwordx4 v[96:97], v[88:91], off
	global_store_dwordx4 v[98:99], v[82:85], off
	s_and_saveexec_b64 s[24:25], s[6:7]
	s_cbranch_execz .LBB0_2189
	s_waitcnt lgkmcnt(0)
	v_add_f32_e32 v80, v80, v81
	v_mov_b32_e32 v242, v80
.LBB0_2189:
	s_or_b64 exec, exec, s[24:25]
	s_waitcnt vmcnt(7)
	v_lshlrev_b32_e32 v84, 16, v132
	v_and_b32_e32 v85, 0xffff0000, v132
	v_lshlrev_b32_e32 v86, 16, v133
	v_and_b32_e32 v87, 0xffff0000, v133
	v_pk_fma_f32 v[78:79], v[78:79], 0.5, v[86:87] op_sel_hi:[1,0,1]
	v_pk_fma_f32 v[76:77], v[76:77], 0.5, v[84:85] op_sel_hi:[1,0,1]
	v_lshlrev_b32_e32 v84, 16, v134
	v_and_b32_e32 v85, 0xffff0000, v134
	v_lshlrev_b32_e32 v86, 16, v135
	v_and_b32_e32 v87, 0xffff0000, v135
	v_pk_fma_f32 v[86:87], v[74:75], 0.5, v[86:87] op_sel_hi:[1,0,1]
	v_pk_fma_f32 v[74:75], v[72:73], 0.5, v[84:85] op_sel_hi:[1,0,1]
	v_cvt_pk_bf16_f32 v72, v76, v77
	v_mul_f32_e32 v77, v77, v77
	v_fmac_f32_e32 v77, v76, v76
	v_mul_f32_e32 v76, v79, v79
	v_fmac_f32_e32 v76, v78, v78
	v_add_f32_e32 v76, v77, v76
	v_mul_f32_e32 v77, v75, v75
	v_fmac_f32_e32 v77, v74, v74
	v_add_f32_e32 v76, v77, v76
	v_mul_f32_e32 v77, v87, v87
	v_fmac_f32_e32 v77, v86, v86
	v_cvt_pk_bf16_f32 v73, v78, v79
	v_add_f32_e32 v84, v77, v76
	s_waitcnt vmcnt(6)
	v_lshlrev_b32_e32 v76, 16, v128
	v_and_b32_e32 v77, 0xffff0000, v128
	v_lshlrev_b32_e32 v78, 16, v129
	v_and_b32_e32 v79, 0xffff0000, v129
	v_pk_fma_f32 v[70:71], v[70:71], 0.5, v[78:79] op_sel_hi:[1,0,1]
	v_pk_fma_f32 v[68:69], v[68:69], 0.5, v[76:77] op_sel_hi:[1,0,1]
	v_lshlrev_b32_e32 v76, 16, v130
	v_and_b32_e32 v77, 0xffff0000, v130
	v_pk_fma_f32 v[76:77], v[64:65], 0.5, v[76:77] op_sel_hi:[1,0,1]
	v_mul_f32_e32 v64, v69, v69
	v_mul_f32_e32 v65, v71, v71
	v_fmac_f32_e32 v64, v68, v68
	v_fmac_f32_e32 v65, v70, v70
	v_lshlrev_b32_e32 v78, 16, v131
	v_and_b32_e32 v79, 0xffff0000, v131
	v_add_f32_e32 v64, v64, v65
	v_mul_f32_e32 v65, v77, v77
	v_pk_fma_f32 v[78:79], v[66:67], 0.5, v[78:79] op_sel_hi:[1,0,1]
	v_fmac_f32_e32 v65, v76, v76
	v_add_f32_e32 v64, v65, v64
	v_mul_f32_e32 v65, v79, v79
	v_fmac_f32_e32 v65, v78, v78
	v_add_f32_e32 v64, v65, v64
	v_add_f32_e32 v64, v84, v64
	ds_bpermute_b32 v65, v184, v64
	s_mov_b64 s[24:25], 0x18000
	s_waitcnt lgkmcnt(1)
	v_lshl_add_u64 v[80:81], v[166:167], 0, s[24:25]
	s_mov_b64 s[24:25], 0x18100
	v_lshl_add_u64 v[82:83], v[166:167], 0, s[24:25]
	s_waitcnt lgkmcnt(0)
	v_add_f32_e32 v64, v64, v65
	ds_bpermute_b32 v65, v185, v64
	v_cvt_pk_bf16_f32 v74, v74, v75
	v_cvt_pk_bf16_f32 v75, v86, v87
	v_cvt_pk_bf16_f32 v66, v68, v69
	v_cvt_pk_bf16_f32 v67, v70, v71
	v_cvt_pk_bf16_f32 v68, v76, v77
	v_cvt_pk_bf16_f32 v69, v78, v79
	global_store_dwordx4 v[80:81], v[72:75], off
	global_store_dwordx4 v[82:83], v[66:69], off
	s_and_saveexec_b64 s[24:25], s[6:7]
	s_cbranch_execz .LBB0_2191
	s_waitcnt lgkmcnt(0)
	v_add_f32_e32 v64, v64, v65
	v_mov_b32_e32 v243, v64

; __device__ __forceinline__ unsigned pk2(float lo, float hi) { f32x2 v = {lo, hi}; bf16x2_t b = __builtin_convertvector(v, bf16x2_t); return __builtin_bit_cast(unsigned, b); }
; __device__ __forceinline__ float bflo(unsigned w) { return __uint_as_float(w << 16); }
;     __device__ __forceinline__ void operator()(const f32x4 (&acc)[2][2][4][2], const Unit& u, int wr, int wc, int fr_, int fq_) const {
;     ...
;             for (int mi = 0; mi < MB; ++mi) {
;                 const int m = mb0 + mi;
;                 const size_t ro = (size_t)(ai * 128 + m * 16) * DM;
;                 const float rs = (MODE == 1) ? __builtin_amdgcn_rsqf(rsv[ai * 4 + m] * (1.0f / 1024.0f) + EPS) : 0.f; float ss = 0.f;
; #pragma unroll
;                 for (int bj = 0; bj < 2; ++bj) {
;                     const u32x4 xq = xw[mi][bj];
;                     f32x4 a0 = acc[ai][bj][m][0], a1 = acc[ai][bj][m][1];
;                     if (MODE == 1) {
;                         const u32x4 uu = uw[mi][bj];
;                         a0[0] = sigm_f(a0[0] * rs) * bflo(uu.x); a0[1] = sigm_f(a0[1] * rs) * bfhi(uu.x); a0[2] = sigm_f(a0[2] * rs) * bflo(uu.y); a0[3] = sigm_f(a0[3] * rs) * bfhi(uu.y);
;                         a1[0] = sigm_f(a1[0] * rs) * bflo(uu.z); a1[1] = sigm_f(a1[1] * rs) * bfhi(uu.z); a1[2] = sigm_f(a1[2] * rs) * bflo(uu.w); a1[3] = sigm_f(a1[3] * rs) * bfhi(uu.w);
;                     } else { a0 = a0 * scale; a1 = a1 * scale; }
;                     const f32x4 v0 = (f32x4){bflo(xq.x), bfhi(xq.x), bflo(xq.y), bfhi(xq.y)} + a0, v1 = (f32x4){bflo(xq.z), bfhi(xq.z), bflo(xq.w), bfhi(xq.w)} + a1;
;                     if (yout) { *(GAS f32x4*)(yp + ro + bj * 128) = v0; *(GAS f32x4*)(yp + ro + bj * 128 + 4) = v1; }
;                     else {
;                         u32x4 w; w.x = pk2(v0[0], v0[1]); w.y = pk2(v0[2], v0[3]); w.z = pk2(v1[0], v1[1]); w.w = pk2(v1[2], v1[3]);
;                         *(GAS u32x4*)(xop + ro + bj * 128) = w;
;                         ss += (v0[0] * v0[0] + v0[1] * v0[1]) + (v0[2] * v0[2] + v0[3] * v0[3]) + (v1[0] * v1[0] + v1[1] * v1[1]) + (v1[2] * v1[2] + v1[3] * v1[3]);
;                     }
;                 }
;                 if (!yout) { ss += __shfl_xor(ss, 16); ss += __shfl_xor(ss, 32);
;                     if (fq == 0) __hip_atomic_fetch_add(sn + ai * 128 + m * 16, ss, __ATOMIC_RELAXED, __HIP_MEMORY_SCOPE_AGENT); }
.LBB0_2197:
	s_or_b64 exec, exec, s[24:25]
	s_waitcnt vmcnt(7)
	v_lshlrev_b32_e32 v20, 16, v68
	v_and_b32_e32 v21, 0xffff0000, v68
	v_lshlrev_b32_e32 v22, 16, v69
	v_and_b32_e32 v23, 0xffff0000, v69
	v_pk_fma_f32 v[14:15], v[14:15], 0.5, v[22:23] op_sel_hi:[1,0,1]
	v_pk_fma_f32 v[12:13], v[12:13], 0.5, v[20:21] op_sel_hi:[1,0,1]
	v_lshlrev_b32_e32 v20, 16, v70
	v_and_b32_e32 v21, 0xffff0000, v70
	v_lshlrev_b32_e32 v22, 16, v71
	v_and_b32_e32 v23, 0xffff0000, v71
	v_pk_fma_f32 v[22:23], v[10:11], 0.5, v[22:23] op_sel_hi:[1,0,1]
	v_pk_fma_f32 v[10:11], v[8:9], 0.5, v[20:21] op_sel_hi:[1,0,1]
	v_cvt_pk_bf16_f32 v8, v12, v13
	v_mul_f32_e32 v13, v13, v13
	v_fmac_f32_e32 v13, v12, v12
	v_mul_f32_e32 v12, v15, v15
	v_fmac_f32_e32 v12, v14, v14
	v_add_f32_e32 v12, v13, v12
	v_mul_f32_e32 v13, v11, v11
	v_fmac_f32_e32 v13, v10, v10
	v_add_f32_e32 v12, v13, v12
	v_mul_f32_e32 v13, v23, v23
	v_fmac_f32_e32 v13, v22, v22
	v_cvt_pk_bf16_f32 v9, v14, v15
	v_add_f32_e32 v20, v13, v12
	s_waitcnt vmcnt(6)
	s_and_saveexec_b64 s[24:25], s[6:7]
	global_atomic_add_f32 v[164:165], v240, off
	global_atomic_add_f32 v[164:165], v241, off offset:64
	global_atomic_add_f32 v[164:165], v242, off offset:128
	global_atomic_add_f32 v[164:165], v243, off offset:192
	s_or_b64 exec, exec, s[24:25]
	v_lshlrev_b32_e32 v12, 16, v64
	v_and_b32_e32 v13, 0xffff0000, v64
	v_lshlrev_b32_e32 v14, 16, v65
	v_and_b32_e32 v15, 0xffff0000, v65
	v_pk_fma_f32 v[6:7], v[6:7], 0.5, v[14:15] op_sel_hi:[1,0,1]
	v_pk_fma_f32 v[4:5], v[4:5], 0.5, v[12:13] op_sel_hi:[1,0,1]
	v_lshlrev_b32_e32 v12, 16, v66
	v_and_b32_e32 v13, 0xffff0000, v66
	v_pk_fma_f32 v[12:13], v[0:1], 0.5, v[12:13] op_sel_hi:[1,0,1]
	v_mul_f32_e32 v0, v5, v5
	v_mul_f32_e32 v1, v7, v7
	v_fmac_f32_e32 v0, v4, v4
	v_fmac_f32_e32 v1, v6, v6
	v_lshlrev_b32_e32 v14, 16, v67
	v_and_b32_e32 v15, 0xffff0000, v67
	v_add_f32_e32 v0, v0, v1
	v_mul_f32_e32 v1, v13, v13
	v_pk_fma_f32 v[14:15], v[2:3], 0.5, v[14:15] op_sel_hi:[1,0,1]
	v_fmac_f32_e32 v1, v12, v12
	v_add_f32_e32 v0, v1, v0
	v_mul_f32_e32 v1, v15, v15
	v_fmac_f32_e32 v1, v14, v14
	v_add_f32_e32 v0, v1, v0
	v_add_f32_e32 v0, v20, v0
	ds_bpermute_b32 v1, v184, v0
	s_mov_b64 s[24:25], 0x58000
	s_waitcnt lgkmcnt(1)
	v_lshl_add_u64 v[16:17], v[166:167], 0, s[24:25]
	s_mov_b64 s[24:25], 0x58100
	v_lshl_add_u64 v[18:19], v[166:167], 0, s[24:25]
	s_waitcnt lgkmcnt(0)
	v_add_f32_e32 v0, v0, v1
	ds_bpermute_b32 v1, v185, v0
	v_cvt_pk_bf16_f32 v10, v10, v11
	v_cvt_pk_bf16_f32 v11, v22, v23
	v_cvt_pk_bf16_f32 v2, v4, v5
	v_cvt_pk_bf16_f32 v3, v6, v7
	v_cvt_pk_bf16_f32 v4, v12, v13
	v_cvt_pk_bf16_f32 v5, v14, v15
	global_store_dwordx4 v[16:17], v[8:11], off
	global_store_dwordx4 v[18:19], v[2:5], off
	s_and_saveexec_b64 s[24:25], s[6:7]
	s_cbranch_execz .LBB0_2199
	s_waitcnt lgkmcnt(0)
	v_add_f32_e32 v0, v0, v1
	global_atomic_add_f32 v[164:165], v0, off offset:704
